# EpiRes epilogues of P9 P11 P14 P16: all 16 hb loads hoisted to epilogue top, counted vmcnt
# baseline (speedup 1.0000x reference)
.LBB0_1180:
	v_lshl_add_u32 v148, s47, 8, v151
	v_ashrrev_i32_e32 v149, 31, v148
	v_lshl_or_b32 v146, s48, 8, v153
	v_lshlrev_b64 v[158:159], 11, v[148:149]
	v_ashrrev_i32_e32 v147, 31, v146
	v_lshl_add_u64 v[158:159], s[92:93], 0, v[158:159]
	v_lshl_add_u64 v[162:163], v[146:147], 1, v[158:159]
	global_load_dwordx4 v[172:175], v[162:163], off
	global_load_dwordx4 v[182:185], v[162:163], off offset:256
	v_or_b32_e32 v176, 16, v148
	v_ashrrev_i32_e32 v177, 31, v176
	v_lshlrev_b64 v[242:243], 11, v[176:177]
	v_lshl_add_u64 v[242:243], s[92:93], 0, v[242:243]
	v_lshl_add_u64 v[246:247], v[146:147], 1, v[242:243]
	global_load_dwordx4 v[186:189], v[246:247], off
	global_load_dwordx4 v[190:193], v[246:247], off offset:256
	v_or_b32_e32 v252, 32, v148
	v_ashrrev_i32_e32 v253, 31, v252
	v_lshlrev_b64 v[254:255], 11, v[252:253]
	v_lshl_add_u64 v[254:255], s[92:93], 0, v[254:255]
	v_lshl_add_u64 v[176:177], v[146:147], 1, v[254:255]
	global_load_dwordx4 v[194:197], v[176:177], off
	global_load_dwordx4 v[198:201], v[176:177], off offset:256
	v_or_b32_e32 v242, 48, v148
	v_ashrrev_i32_e32 v243, 31, v242
	v_lshlrev_b64 v[246:247], 11, v[242:243]
	v_lshl_add_u64 v[246:247], s[92:93], 0, v[246:247]
	v_lshl_add_u64 v[252:253], v[146:147], 1, v[246:247]
	global_load_dwordx4 v[202:205], v[252:253], off
	global_load_dwordx4 v[206:209], v[252:253], off offset:256
	v_add_u32_e32 v254, 0x80, v148
	v_ashrrev_i32_e32 v255, 31, v254
	v_lshlrev_b64 v[176:177], 11, v[254:255]
	v_lshl_add_u64 v[176:177], s[92:93], 0, v[176:177]
	v_lshl_add_u64 v[242:243], v[146:147], 1, v[176:177]
	global_load_dwordx4 v[210:213], v[242:243], off
	global_load_dwordx4 v[214:217], v[242:243], off offset:256
	v_add_u32_e32 v246, 0x90, v148
	v_ashrrev_i32_e32 v247, 31, v246
	v_lshlrev_b64 v[252:253], 11, v[246:247]
	v_lshl_add_u64 v[252:253], s[92:93], 0, v[252:253]
	v_lshl_add_u64 v[254:255], v[146:147], 1, v[252:253]
	global_load_dwordx4 v[218:221], v[254:255], off
	global_load_dwordx4 v[226:229], v[254:255], off offset:256
	v_add_u32_e32 v176, 0xa0, v148
	v_ashrrev_i32_e32 v177, 31, v176
	v_lshlrev_b64 v[242:243], 11, v[176:177]
	v_lshl_add_u64 v[242:243], s[92:93], 0, v[242:243]
	v_lshl_add_u64 v[246:247], v[146:147], 1, v[242:243]
	global_load_dwordx4 v[230:233], v[246:247], off
	global_load_dwordx4 v[234:237], v[246:247], off offset:256
	v_add_u32_e32 v252, 0xb0, v148
	v_ashrrev_i32_e32 v253, 31, v252
	v_lshlrev_b64 v[254:255], 11, v[252:253]
	v_lshl_add_u64 v[254:255], s[92:93], 0, v[254:255]
	v_lshl_add_u64 v[176:177], v[146:147], 1, v[254:255]
	global_load_dwordx4 v[238:241], v[176:177], off
	global_load_dwordx4 v[248:251], v[176:177], off offset:256
	s_nop 0
	v_xor_b32_e32 v170, 32, v157
	s_waitcnt vmcnt(15)
	v_lshlrev_b32_e32 v164, 16, v172
	v_and_b32_e32 v165, 0xffff0000, v172
	v_lshlrev_b32_e32 v158, 16, v173
	v_and_b32_e32 v159, 0xffff0000, v173
	v_lshlrev_b32_e32 v166, 16, v174
	v_and_b32_e32 v167, 0xffff0000, v174
	v_lshlrev_b32_e32 v160, 16, v175
	v_and_b32_e32 v161, 0xffff0000, v175
	v_pk_fma_f32 v[128:129], v[128:129], 0.5, v[158:159] op_sel_hi:[1,0,1]
	v_pk_fma_f32 v[164:165], v[126:127], 0.5, v[164:165] op_sel_hi:[1,0,1]
	v_pk_fma_f32 v[168:169], v[124:125], 0.5, v[160:161] op_sel_hi:[1,0,1]
	v_pk_fma_f32 v[166:167], v[122:123], 0.5, v[166:167] op_sel_hi:[1,0,1]
	v_cvt_pk_bf16_f32 v124, v164, v165
	v_cvt_pk_bf16_f32 v125, v128, v129
	v_mul_f32_e32 v171, v165, v165
	v_cvt_pk_bf16_f32 v126, v166, v167
	v_cvt_pk_bf16_f32 v127, v168, v169
	s_nop 0
	v_fmac_f32_e32 v171, v164, v164
	v_fmac_f32_e32 v171, v128, v128
	v_fmac_f32_e32 v171, v129, v129
	v_and_b32_e32 v123, 64, v157
	v_fmac_f32_e32 v171, v166, v166
	v_xor_b32_e32 v122, 16, v157
	v_add_u32_e32 v123, 64, v123
	v_fmac_f32_e32 v171, v167, v167
	v_cmp_lt_i32_e32 vcc, v122, v123
	v_fmac_f32_e32 v171, v168, v168
	v_fmac_f32_e32 v171, v169, v169
	v_cndmask_b32_e32 v122, v157, v122, vcc
	v_lshlrev_b32_e32 v122, 2, v122
	v_cmp_lt_i32_e32 vcc, v170, v123
	global_store_dwordx4 v[162:163], v[124:127], off
	s_waitcnt vmcnt(15)
	v_lshlrev_b32_e32 v128, 16, v182
	v_and_b32_e32 v129, 0xffff0000, v182
	v_lshlrev_b32_e32 v158, 16, v183
	v_and_b32_e32 v159, 0xffff0000, v183
	v_lshlrev_b32_e32 v164, 16, v184
	v_and_b32_e32 v165, 0xffff0000, v184
	v_pk_fma_f32 v[118:119], v[118:119], 0.5, v[128:129] op_sel_hi:[1,0,1]
	v_pk_fma_f32 v[120:121], v[120:121], 0.5, v[158:159] op_sel_hi:[1,0,1]
	v_pk_fma_f32 v[158:159], v[114:115], 0.5, v[164:165] op_sel_hi:[1,0,1]
	v_mul_f32_e32 v114, v119, v119
	v_fmac_f32_e32 v114, v118, v118
	v_fmac_f32_e32 v114, v120, v120
	v_fmac_f32_e32 v114, v121, v121
	v_lshlrev_b32_e32 v160, 16, v185
	v_and_b32_e32 v161, 0xffff0000, v185
	v_fmac_f32_e32 v114, v158, v158
	v_pk_fma_f32 v[128:129], v[116:117], 0.5, v[160:161] op_sel_hi:[1,0,1]
	v_fmac_f32_e32 v114, v159, v159
	v_fmac_f32_e32 v114, v128, v128
	v_fmac_f32_e32 v114, v129, v129
	v_add_f32_e32 v114, v171, v114
	ds_bpermute_b32 v115, v122, v114
	v_cndmask_b32_e32 v116, v157, v170, vcc
	v_lshlrev_b32_e32 v116, 2, v116
	v_cvt_pk_bf16_f32 v118, v118, v119
	v_cvt_pk_bf16_f32 v119, v120, v121
	s_waitcnt lgkmcnt(0)
	v_add_f32_e32 v114, v114, v115
	ds_bpermute_b32 v115, v116, v114
	v_cvt_pk_bf16_f32 v120, v158, v159
	v_cvt_pk_bf16_f32 v121, v128, v129
	global_store_dwordx4 v[162:163], v[118:121], off offset:256
	s_and_saveexec_b64 s[20:21], s[2:3]
	s_cbranch_execz .LBB0_1182
	v_lshl_add_u64 v[118:119], v[148:149], 2, s[12:13]
	s_waitcnt lgkmcnt(0)
	v_add_f32_e32 v114, v114, v115
	global_atomic_add_f32 v[118:119], v114, off
.LBB0_1182:
	s_or_b64 exec, exec, s[20:21]
	v_or_b32_e32 v114, 16, v148
	s_waitcnt lgkmcnt(0)
	v_ashrrev_i32_e32 v115, 31, v114
	v_lshlrev_b64 v[118:119], 11, v[114:115]
	v_lshl_add_u64 v[118:119], s[92:93], 0, v[118:119]
	v_lshl_add_u64 v[124:125], v[146:147], 1, v[118:119]
	s_nop 0
	s_waitcnt vmcnt(15)
	v_lshlrev_b32_e32 v126, 16, v186
	v_and_b32_e32 v127, 0xffff0000, v186
	v_lshlrev_b32_e32 v118, 16, v187
	v_and_b32_e32 v119, 0xffff0000, v187
	v_lshlrev_b32_e32 v128, 16, v188
	v_and_b32_e32 v129, 0xffff0000, v188
	v_lshlrev_b32_e32 v120, 16, v189
	v_and_b32_e32 v121, 0xffff0000, v189
	v_pk_fma_f32 v[118:119], v[112:113], 0.5, v[118:119] op_sel_hi:[1,0,1]
	v_pk_fma_f32 v[126:127], v[110:111], 0.5, v[126:127] op_sel_hi:[1,0,1]
	v_pk_fma_f32 v[120:121], v[108:109], 0.5, v[120:121] op_sel_hi:[1,0,1]
	v_pk_fma_f32 v[128:129], v[106:107], 0.5, v[128:129] op_sel_hi:[1,0,1]
	v_cvt_pk_bf16_f32 v106, v126, v127
	v_cvt_pk_bf16_f32 v107, v118, v119
	v_mul_f32_e32 v117, v127, v127
	v_cvt_pk_bf16_f32 v108, v128, v129
	v_cvt_pk_bf16_f32 v109, v120, v121
	s_nop 0
	v_fmac_f32_e32 v117, v126, v126
	v_fmac_f32_e32 v117, v118, v118
	v_fmac_f32_e32 v117, v119, v119
	v_fmac_f32_e32 v117, v128, v128
	v_fmac_f32_e32 v117, v129, v129
	v_fmac_f32_e32 v117, v120, v120
	v_fmac_f32_e32 v117, v121, v121
	global_store_dwordx4 v[124:125], v[106:109], off
	s_waitcnt vmcnt(15)
	v_lshlrev_b32_e32 v118, 16, v190
	v_and_b32_e32 v119, 0xffff0000, v190
	v_lshlrev_b32_e32 v110, 16, v191
	v_and_b32_e32 v111, 0xffff0000, v191
	v_lshlrev_b32_e32 v120, 16, v192
	v_and_b32_e32 v121, 0xffff0000, v192
	v_lshlrev_b32_e32 v112, 16, v193
	v_and_b32_e32 v113, 0xffff0000, v193
	v_pk_fma_f32 v[102:103], v[102:103], 0.5, v[118:119] op_sel_hi:[1,0,1]
	v_pk_fma_f32 v[104:105], v[104:105], 0.5, v[110:111] op_sel_hi:[1,0,1]
	v_pk_fma_f32 v[110:111], v[100:101], 0.5, v[112:113] op_sel_hi:[1,0,1]
	v_pk_fma_f32 v[112:113], v[98:99], 0.5, v[120:121] op_sel_hi:[1,0,1]
	v_mul_f32_e32 v98, v103, v103
	v_fmac_f32_e32 v98, v102, v102
	v_fmac_f32_e32 v98, v104, v104
	v_fmac_f32_e32 v98, v105, v105
	v_fmac_f32_e32 v98, v112, v112
	v_fmac_f32_e32 v98, v113, v113
	v_fmac_f32_e32 v98, v110, v110
	v_fmac_f32_e32 v98, v111, v111
	v_add_f32_e32 v98, v117, v98
	ds_bpermute_b32 v99, v122, v98
	v_cvt_pk_bf16_f32 v100, v102, v103
	v_cvt_pk_bf16_f32 v101, v104, v105
	v_cvt_pk_bf16_f32 v102, v112, v113
	v_cvt_pk_bf16_f32 v103, v110, v111
	s_waitcnt lgkmcnt(0)
	v_add_f32_e32 v98, v98, v99
	ds_bpermute_b32 v99, v116, v98
	global_store_dwordx4 v[124:125], v[100:103], off offset:256
	s_and_saveexec_b64 s[20:21], s[2:3]
	s_cbranch_execz .LBB0_1184
	v_lshl_add_u64 v[100:101], v[114:115], 2, s[12:13]
	s_waitcnt lgkmcnt(0)
	v_add_f32_e32 v98, v98, v99
	global_atomic_add_f32 v[100:101], v98, off
.LBB0_1184:
	s_or_b64 exec, exec, s[20:21]
	v_or_b32_e32 v98, 32, v148
	s_waitcnt lgkmcnt(0)
	v_ashrrev_i32_e32 v99, 31, v98
	v_lshlrev_b64 v[100:101], 11, v[98:99]
	v_lshl_add_u64 v[100:101], s[92:93], 0, v[100:101]
	v_lshl_add_u64 v[104:105], v[146:147], 1, v[100:101]
	s_nop 0
	s_waitcnt vmcnt(15)
	v_lshlrev_b32_e32 v106, 16, v194
	v_and_b32_e32 v107, 0xffff0000, v194
	v_lshlrev_b32_e32 v100, 16, v195
	v_and_b32_e32 v101, 0xffff0000, v195
	v_lshlrev_b32_e32 v108, 16, v196
	v_and_b32_e32 v109, 0xffff0000, v196
	v_lshlrev_b32_e32 v102, 16, v197
	v_and_b32_e32 v103, 0xffff0000, v197
	v_pk_fma_f32 v[100:101], v[96:97], 0.5, v[100:101] op_sel_hi:[1,0,1]
	v_pk_fma_f32 v[106:107], v[94:95], 0.5, v[106:107] op_sel_hi:[1,0,1]
	v_pk_fma_f32 v[102:103], v[92:93], 0.5, v[102:103] op_sel_hi:[1,0,1]
	v_pk_fma_f32 v[108:109], v[90:91], 0.5, v[108:109] op_sel_hi:[1,0,1]
	v_cvt_pk_bf16_f32 v90, v106, v107
	v_cvt_pk_bf16_f32 v91, v100, v101
	v_mul_f32_e32 v107, v107, v107
	v_cvt_pk_bf16_f32 v92, v108, v109
	v_cvt_pk_bf16_f32 v93, v102, v103
	s_nop 0
	v_fmac_f32_e32 v107, v106, v106
	v_fmac_f32_e32 v107, v100, v100
	v_fmac_f32_e32 v107, v101, v101
	v_fmac_f32_e32 v107, v108, v108
	v_fmac_f32_e32 v107, v109, v109
	v_fmac_f32_e32 v107, v102, v102
	v_fmac_f32_e32 v107, v103, v103
	global_store_dwordx4 v[104:105], v[90:93], off
	s_waitcnt vmcnt(15)
	v_lshlrev_b32_e32 v100, 16, v198
	v_and_b32_e32 v101, 0xffff0000, v198
	v_lshlrev_b32_e32 v94, 16, v199
	v_and_b32_e32 v95, 0xffff0000, v199
	v_lshlrev_b32_e32 v102, 16, v200
	v_and_b32_e32 v103, 0xffff0000, v200
	v_lshlrev_b32_e32 v96, 16, v201
	v_and_b32_e32 v97, 0xffff0000, v201
	v_pk_fma_f32 v[86:87], v[86:87], 0.5, v[100:101] op_sel_hi:[1,0,1]
	v_pk_fma_f32 v[88:89], v[88:89], 0.5, v[94:95] op_sel_hi:[1,0,1]
	v_pk_fma_f32 v[94:95], v[84:85], 0.5, v[96:97] op_sel_hi:[1,0,1]
	v_pk_fma_f32 v[96:97], v[82:83], 0.5, v[102:103] op_sel_hi:[1,0,1]
	v_mul_f32_e32 v82, v87, v87
	v_fmac_f32_e32 v82, v86, v86
	v_fmac_f32_e32 v82, v88, v88
	v_fmac_f32_e32 v82, v89, v89
	v_fmac_f32_e32 v82, v96, v96
	v_fmac_f32_e32 v82, v97, v97
	v_fmac_f32_e32 v82, v94, v94
	v_fmac_f32_e32 v82, v95, v95
	v_add_f32_e32 v82, v107, v82
	ds_bpermute_b32 v83, v122, v82
	v_cvt_pk_bf16_f32 v84, v86, v87
	v_cvt_pk_bf16_f32 v85, v88, v89
	v_cvt_pk_bf16_f32 v86, v96, v97
	v_cvt_pk_bf16_f32 v87, v94, v95
	s_waitcnt lgkmcnt(0)
	v_add_f32_e32 v82, v82, v83
	ds_bpermute_b32 v83, v116, v82
	global_store_dwordx4 v[104:105], v[84:87], off offset:256
	s_and_saveexec_b64 s[20:21], s[2:3]
	s_cbranch_execz .LBB0_1186
	v_lshl_add_u64 v[84:85], v[98:99], 2, s[12:13]
	s_waitcnt lgkmcnt(0)
	v_add_f32_e32 v82, v82, v83
	global_atomic_add_f32 v[84:85], v82, off
.LBB0_1186:
	s_or_b64 exec, exec, s[20:21]
	v_or_b32_e32 v82, 48, v148
	s_waitcnt lgkmcnt(0)
	v_ashrrev_i32_e32 v83, 31, v82
	v_lshlrev_b64 v[84:85], 11, v[82:83]
	v_lshl_add_u64 v[84:85], s[92:93], 0, v[84:85]
	v_lshl_add_u64 v[88:89], v[146:147], 1, v[84:85]
	s_nop 0
	s_waitcnt vmcnt(15)
	v_lshlrev_b32_e32 v90, 16, v202
	v_and_b32_e32 v91, 0xffff0000, v202
	v_lshlrev_b32_e32 v84, 16, v203
	v_and_b32_e32 v85, 0xffff0000, v203
	v_lshlrev_b32_e32 v92, 16, v204
	v_and_b32_e32 v93, 0xffff0000, v204
	v_lshlrev_b32_e32 v86, 16, v205
	v_and_b32_e32 v87, 0xffff0000, v205
	v_pk_fma_f32 v[84:85], v[80:81], 0.5, v[84:85] op_sel_hi:[1,0,1]
	v_pk_fma_f32 v[90:91], v[78:79], 0.5, v[90:91] op_sel_hi:[1,0,1]
	v_pk_fma_f32 v[86:87], v[76:77], 0.5, v[86:87] op_sel_hi:[1,0,1]
	v_pk_fma_f32 v[92:93], v[74:75], 0.5, v[92:93] op_sel_hi:[1,0,1]
	v_cvt_pk_bf16_f32 v74, v90, v91
	v_cvt_pk_bf16_f32 v75, v84, v85
	v_mul_f32_e32 v91, v91, v91
	v_cvt_pk_bf16_f32 v76, v92, v93
	v_cvt_pk_bf16_f32 v77, v86, v87
	s_nop 0
	v_fmac_f32_e32 v91, v90, v90
	v_fmac_f32_e32 v91, v84, v84
	v_fmac_f32_e32 v91, v85, v85
	v_fmac_f32_e32 v91, v92, v92
	v_fmac_f32_e32 v91, v93, v93
	v_fmac_f32_e32 v91, v86, v86
	v_fmac_f32_e32 v91, v87, v87
	global_store_dwordx4 v[88:89], v[74:77], off
	s_waitcnt vmcnt(15)
	v_lshlrev_b32_e32 v84, 16, v206
	v_and_b32_e32 v85, 0xffff0000, v206
	v_lshlrev_b32_e32 v78, 16, v207
	v_and_b32_e32 v79, 0xffff0000, v207
	v_lshlrev_b32_e32 v86, 16, v208
	v_and_b32_e32 v87, 0xffff0000, v208
	v_lshlrev_b32_e32 v80, 16, v209
	v_and_b32_e32 v81, 0xffff0000, v209
	v_pk_fma_f32 v[70:71], v[70:71], 0.5, v[84:85] op_sel_hi:[1,0,1]
	v_pk_fma_f32 v[72:73], v[72:73], 0.5, v[78:79] op_sel_hi:[1,0,1]
	v_pk_fma_f32 v[78:79], v[68:69], 0.5, v[80:81] op_sel_hi:[1,0,1]
	v_pk_fma_f32 v[80:81], v[66:67], 0.5, v[86:87] op_sel_hi:[1,0,1]
	v_mul_f32_e32 v66, v71, v71
	v_fmac_f32_e32 v66, v70, v70
	v_fmac_f32_e32 v66, v72, v72
	v_fmac_f32_e32 v66, v73, v73
	v_fmac_f32_e32 v66, v80, v80
	v_fmac_f32_e32 v66, v81, v81
	v_fmac_f32_e32 v66, v78, v78
	v_fmac_f32_e32 v66, v79, v79
	v_add_f32_e32 v66, v91, v66
	ds_bpermute_b32 v67, v122, v66
	v_cvt_pk_bf16_f32 v68, v70, v71
	v_cvt_pk_bf16_f32 v69, v72, v73
	v_cvt_pk_bf16_f32 v70, v80, v81
	v_cvt_pk_bf16_f32 v71, v78, v79
	s_waitcnt lgkmcnt(0)
	v_add_f32_e32 v66, v66, v67
	ds_bpermute_b32 v67, v116, v66
	global_store_dwordx4 v[88:89], v[68:71], off offset:256
	s_and_saveexec_b64 s[20:21], s[2:3]
	s_cbranch_execz .LBB0_1188
	v_lshl_add_u64 v[68:69], v[82:83], 2, s[12:13]
	s_waitcnt lgkmcnt(0)
	v_add_f32_e32 v66, v66, v67
	global_atomic_add_f32 v[68:69], v66, off
.LBB0_1188:
	s_or_b64 exec, exec, s[20:21]
	v_add_u32_e32 v66, 0x80, v148
	s_waitcnt lgkmcnt(0)
	v_ashrrev_i32_e32 v67, 31, v66
	v_lshlrev_b64 v[68:69], 11, v[66:67]
	v_lshl_add_u64 v[68:69], s[92:93], 0, v[68:69]
	v_lshl_add_u64 v[72:73], v[146:147], 1, v[68:69]
	s_nop 0
	s_waitcnt vmcnt(15)
	v_lshlrev_b32_e32 v74, 16, v210
	v_and_b32_e32 v75, 0xffff0000, v210
	v_lshlrev_b32_e32 v68, 16, v211
	v_and_b32_e32 v69, 0xffff0000, v211
	v_lshlrev_b32_e32 v76, 16, v212
	v_and_b32_e32 v77, 0xffff0000, v212
	v_lshlrev_b32_e32 v70, 16, v213
	v_and_b32_e32 v71, 0xffff0000, v213
	v_pk_fma_f32 v[68:69], v[64:65], 0.5, v[68:69] op_sel_hi:[1,0,1]
	v_pk_fma_f32 v[74:75], v[62:63], 0.5, v[74:75] op_sel_hi:[1,0,1]
	v_pk_fma_f32 v[70:71], v[60:61], 0.5, v[70:71] op_sel_hi:[1,0,1]
	v_pk_fma_f32 v[76:77], v[58:59], 0.5, v[76:77] op_sel_hi:[1,0,1]
	v_cvt_pk_bf16_f32 v58, v74, v75
	v_cvt_pk_bf16_f32 v59, v68, v69
	v_mul_f32_e32 v75, v75, v75
	v_cvt_pk_bf16_f32 v60, v76, v77
	v_cvt_pk_bf16_f32 v61, v70, v71
	s_nop 0
	v_fmac_f32_e32 v75, v74, v74
	v_fmac_f32_e32 v75, v68, v68
	v_fmac_f32_e32 v75, v69, v69
	v_fmac_f32_e32 v75, v76, v76
	v_fmac_f32_e32 v75, v77, v77
	v_fmac_f32_e32 v75, v70, v70
	v_fmac_f32_e32 v75, v71, v71
	global_store_dwordx4 v[72:73], v[58:61], off
	s_waitcnt vmcnt(15)
	v_lshlrev_b32_e32 v68, 16, v214
	v_and_b32_e32 v69, 0xffff0000, v214
	v_lshlrev_b32_e32 v62, 16, v215
	v_and_b32_e32 v63, 0xffff0000, v215
	v_lshlrev_b32_e32 v70, 16, v216
	v_and_b32_e32 v71, 0xffff0000, v216
	v_lshlrev_b32_e32 v64, 16, v217
	v_and_b32_e32 v65, 0xffff0000, v217
	v_pk_fma_f32 v[54:55], v[54:55], 0.5, v[68:69] op_sel_hi:[1,0,1]
	v_pk_fma_f32 v[56:57], v[56:57], 0.5, v[62:63] op_sel_hi:[1,0,1]
	v_pk_fma_f32 v[62:63], v[52:53], 0.5, v[64:65] op_sel_hi:[1,0,1]
	v_pk_fma_f32 v[64:65], v[50:51], 0.5, v[70:71] op_sel_hi:[1,0,1]
	v_mul_f32_e32 v50, v55, v55
	v_fmac_f32_e32 v50, v54, v54
	v_fmac_f32_e32 v50, v56, v56
	v_fmac_f32_e32 v50, v57, v57
	v_fmac_f32_e32 v50, v64, v64
	v_fmac_f32_e32 v50, v65, v65
	v_fmac_f32_e32 v50, v62, v62
	v_fmac_f32_e32 v50, v63, v63
	v_add_f32_e32 v50, v75, v50
	ds_bpermute_b32 v51, v122, v50
	v_cvt_pk_bf16_f32 v52, v54, v55
	v_cvt_pk_bf16_f32 v53, v56, v57
	v_cvt_pk_bf16_f32 v54, v64, v65
	v_cvt_pk_bf16_f32 v55, v62, v63
	s_waitcnt lgkmcnt(0)
	v_add_f32_e32 v50, v50, v51
	ds_bpermute_b32 v51, v116, v50
	global_store_dwordx4 v[72:73], v[52:55], off offset:256
	s_and_saveexec_b64 s[20:21], s[2:3]
	s_cbranch_execz .LBB0_1190
	v_lshl_add_u64 v[52:53], v[66:67], 2, s[12:13]
	s_waitcnt lgkmcnt(0)
	v_add_f32_e32 v50, v50, v51
	global_atomic_add_f32 v[52:53], v50, off
.LBB0_1190:
	s_or_b64 exec, exec, s[20:21]
	v_add_u32_e32 v50, 0x90, v148
	s_waitcnt lgkmcnt(0)
	v_ashrrev_i32_e32 v51, 31, v50
	v_lshlrev_b64 v[52:53], 11, v[50:51]
	v_lshl_add_u64 v[52:53], s[92:93], 0, v[52:53]
	v_lshl_add_u64 v[56:57], v[146:147], 1, v[52:53]
	s_nop 0
	s_waitcnt vmcnt(15)
	v_lshlrev_b32_e32 v58, 16, v218
	v_and_b32_e32 v59, 0xffff0000, v218
	v_lshlrev_b32_e32 v52, 16, v219
	v_and_b32_e32 v53, 0xffff0000, v219
	v_lshlrev_b32_e32 v60, 16, v220
	v_and_b32_e32 v61, 0xffff0000, v220
	v_lshlrev_b32_e32 v54, 16, v221
	v_and_b32_e32 v55, 0xffff0000, v221
	v_pk_fma_f32 v[52:53], v[48:49], 0.5, v[52:53] op_sel_hi:[1,0,1]
	v_pk_fma_f32 v[58:59], v[46:47], 0.5, v[58:59] op_sel_hi:[1,0,1]
	v_pk_fma_f32 v[54:55], v[44:45], 0.5, v[54:55] op_sel_hi:[1,0,1]
	v_pk_fma_f32 v[60:61], v[42:43], 0.5, v[60:61] op_sel_hi:[1,0,1]
	v_cvt_pk_bf16_f32 v42, v58, v59
	v_cvt_pk_bf16_f32 v43, v52, v53
	v_mul_f32_e32 v59, v59, v59
	v_cvt_pk_bf16_f32 v44, v60, v61
	v_cvt_pk_bf16_f32 v45, v54, v55
	s_nop 0
	v_fmac_f32_e32 v59, v58, v58
	v_fmac_f32_e32 v59, v52, v52
	v_fmac_f32_e32 v59, v53, v53
	v_fmac_f32_e32 v59, v60, v60
	v_fmac_f32_e32 v59, v61, v61
	v_fmac_f32_e32 v59, v54, v54
	v_fmac_f32_e32 v59, v55, v55
	global_store_dwordx4 v[56:57], v[42:45], off
	s_waitcnt vmcnt(15)
	v_lshlrev_b32_e32 v52, 16, v226
	v_and_b32_e32 v53, 0xffff0000, v226
	v_lshlrev_b32_e32 v46, 16, v227
	v_and_b32_e32 v47, 0xffff0000, v227
	v_lshlrev_b32_e32 v54, 16, v228
	v_and_b32_e32 v55, 0xffff0000, v228
	v_lshlrev_b32_e32 v48, 16, v229
	v_and_b32_e32 v49, 0xffff0000, v229
	v_pk_fma_f32 v[38:39], v[38:39], 0.5, v[52:53] op_sel_hi:[1,0,1]
	v_pk_fma_f32 v[40:41], v[40:41], 0.5, v[46:47] op_sel_hi:[1,0,1]
	v_pk_fma_f32 v[46:47], v[36:37], 0.5, v[48:49] op_sel_hi:[1,0,1]
	v_pk_fma_f32 v[48:49], v[34:35], 0.5, v[54:55] op_sel_hi:[1,0,1]
	v_mul_f32_e32 v34, v39, v39
	v_fmac_f32_e32 v34, v38, v38
	v_fmac_f32_e32 v34, v40, v40
	v_fmac_f32_e32 v34, v41, v41
	v_fmac_f32_e32 v34, v48, v48
	v_fmac_f32_e32 v34, v49, v49
	v_fmac_f32_e32 v34, v46, v46
	v_fmac_f32_e32 v34, v47, v47
	v_add_f32_e32 v34, v59, v34
	ds_bpermute_b32 v35, v122, v34
	v_cvt_pk_bf16_f32 v36, v38, v39
	v_cvt_pk_bf16_f32 v37, v40, v41
	v_cvt_pk_bf16_f32 v38, v48, v49
	v_cvt_pk_bf16_f32 v39, v46, v47
	s_waitcnt lgkmcnt(0)
	v_add_f32_e32 v34, v34, v35
	ds_bpermute_b32 v35, v116, v34
	global_store_dwordx4 v[56:57], v[36:39], off offset:256
	s_and_saveexec_b64 s[20:21], s[2:3]
	s_cbranch_execz .LBB0_1192
	v_lshl_add_u64 v[36:37], v[50:51], 2, s[12:13]
	s_waitcnt lgkmcnt(0)
	v_add_f32_e32 v34, v34, v35
	global_atomic_add_f32 v[36:37], v34, off
.LBB0_1192:
	s_or_b64 exec, exec, s[20:21]
	v_add_u32_e32 v34, 0xa0, v148
	s_waitcnt lgkmcnt(0)
	v_ashrrev_i32_e32 v35, 31, v34
	v_lshlrev_b64 v[36:37], 11, v[34:35]
	v_lshl_add_u64 v[36:37], s[92:93], 0, v[36:37]
	v_lshl_add_u64 v[40:41], v[146:147], 1, v[36:37]
	s_nop 0
	s_waitcnt vmcnt(15)
	v_lshlrev_b32_e32 v42, 16, v230
	v_and_b32_e32 v43, 0xffff0000, v230
	v_lshlrev_b32_e32 v36, 16, v231
	v_and_b32_e32 v37, 0xffff0000, v231
	v_lshlrev_b32_e32 v44, 16, v232
	v_and_b32_e32 v45, 0xffff0000, v232
	v_lshlrev_b32_e32 v38, 16, v233
	v_and_b32_e32 v39, 0xffff0000, v233
	v_pk_fma_f32 v[36:37], v[32:33], 0.5, v[36:37] op_sel_hi:[1,0,1]
	v_pk_fma_f32 v[42:43], v[30:31], 0.5, v[42:43] op_sel_hi:[1,0,1]
	v_pk_fma_f32 v[38:39], v[28:29], 0.5, v[38:39] op_sel_hi:[1,0,1]
	v_pk_fma_f32 v[44:45], v[26:27], 0.5, v[44:45] op_sel_hi:[1,0,1]
	v_cvt_pk_bf16_f32 v26, v42, v43
	v_cvt_pk_bf16_f32 v27, v36, v37
	v_mul_f32_e32 v43, v43, v43
	v_cvt_pk_bf16_f32 v28, v44, v45
	v_cvt_pk_bf16_f32 v29, v38, v39
	s_nop 0
	v_fmac_f32_e32 v43, v42, v42
	v_fmac_f32_e32 v43, v36, v36
	v_fmac_f32_e32 v43, v37, v37
	v_fmac_f32_e32 v43, v44, v44
	v_fmac_f32_e32 v43, v45, v45
	v_fmac_f32_e32 v43, v38, v38
	v_fmac_f32_e32 v43, v39, v39
	global_store_dwordx4 v[40:41], v[26:29], off
	s_waitcnt vmcnt(15)
	v_lshlrev_b32_e32 v36, 16, v234
	v_and_b32_e32 v37, 0xffff0000, v234
	v_lshlrev_b32_e32 v30, 16, v235
	v_and_b32_e32 v31, 0xffff0000, v235
	v_lshlrev_b32_e32 v38, 16, v236
	v_and_b32_e32 v39, 0xffff0000, v236
	v_lshlrev_b32_e32 v32, 16, v237
	v_and_b32_e32 v33, 0xffff0000, v237
	v_pk_fma_f32 v[22:23], v[22:23], 0.5, v[36:37] op_sel_hi:[1,0,1]
	v_pk_fma_f32 v[24:25], v[24:25], 0.5, v[30:31] op_sel_hi:[1,0,1]
	v_pk_fma_f32 v[30:31], v[20:21], 0.5, v[32:33] op_sel_hi:[1,0,1]
	v_pk_fma_f32 v[32:33], v[18:19], 0.5, v[38:39] op_sel_hi:[1,0,1]
	v_mul_f32_e32 v18, v23, v23
	v_fmac_f32_e32 v18, v22, v22
	v_fmac_f32_e32 v18, v24, v24
	v_fmac_f32_e32 v18, v25, v25
	v_fmac_f32_e32 v18, v32, v32
	v_fmac_f32_e32 v18, v33, v33
	v_fmac_f32_e32 v18, v30, v30
	v_fmac_f32_e32 v18, v31, v31
	v_add_f32_e32 v18, v43, v18
	ds_bpermute_b32 v19, v122, v18
	v_cvt_pk_bf16_f32 v20, v22, v23
	v_cvt_pk_bf16_f32 v21, v24, v25
	v_cvt_pk_bf16_f32 v22, v32, v33
	v_cvt_pk_bf16_f32 v23, v30, v31
	s_waitcnt lgkmcnt(0)
	v_add_f32_e32 v18, v18, v19
	ds_bpermute_b32 v19, v116, v18
	global_store_dwordx4 v[40:41], v[20:23], off offset:256
	s_and_saveexec_b64 s[20:21], s[2:3]
	s_cbranch_execz .LBB0_1194
	v_lshl_add_u64 v[20:21], v[34:35], 2, s[12:13]
	s_waitcnt lgkmcnt(0)
	v_add_f32_e32 v18, v18, v19
	global_atomic_add_f32 v[20:21], v18, off
.LBB0_1194:
	s_or_b64 exec, exec, s[20:21]
	v_add_u32_e32 v18, 0xb0, v148
	s_waitcnt lgkmcnt(0)
	v_ashrrev_i32_e32 v19, 31, v18
	v_lshlrev_b64 v[20:21], 11, v[18:19]
	v_lshl_add_u64 v[20:21], s[92:93], 0, v[20:21]
	v_lshl_add_u64 v[24:25], v[146:147], 1, v[20:21]
	s_nop 0
	s_waitcnt vmcnt(15)
	v_lshlrev_b32_e32 v26, 16, v238
	v_and_b32_e32 v27, 0xffff0000, v238
	v_lshlrev_b32_e32 v20, 16, v239
	v_and_b32_e32 v21, 0xffff0000, v239
	v_lshlrev_b32_e32 v28, 16, v240
	v_and_b32_e32 v29, 0xffff0000, v240
	v_lshlrev_b32_e32 v22, 16, v241
	v_and_b32_e32 v23, 0xffff0000, v241
	v_pk_fma_f32 v[20:21], v[16:17], 0.5, v[20:21] op_sel_hi:[1,0,1]
	v_pk_fma_f32 v[26:27], v[14:15], 0.5, v[26:27] op_sel_hi:[1,0,1]
	v_pk_fma_f32 v[22:23], v[12:13], 0.5, v[22:23] op_sel_hi:[1,0,1]
	v_pk_fma_f32 v[28:29], v[10:11], 0.5, v[28:29] op_sel_hi:[1,0,1]
	v_cvt_pk_bf16_f32 v10, v26, v27
	v_cvt_pk_bf16_f32 v11, v20, v21
	v_mul_f32_e32 v27, v27, v27
	v_cvt_pk_bf16_f32 v12, v28, v29
	v_cvt_pk_bf16_f32 v13, v22, v23
	s_nop 0
	v_fmac_f32_e32 v27, v26, v26
	v_fmac_f32_e32 v27, v20, v20
	v_fmac_f32_e32 v27, v21, v21
	v_fmac_f32_e32 v27, v28, v28
	v_fmac_f32_e32 v27, v29, v29
	v_fmac_f32_e32 v27, v22, v22
	v_fmac_f32_e32 v27, v23, v23
	global_store_dwordx4 v[24:25], v[10:13], off
	s_waitcnt vmcnt(15)
	v_lshlrev_b32_e32 v20, 16, v248
	v_and_b32_e32 v21, 0xffff0000, v248
	v_lshlrev_b32_e32 v14, 16, v249
	v_and_b32_e32 v15, 0xffff0000, v249
	v_lshlrev_b32_e32 v22, 16, v250
	v_and_b32_e32 v23, 0xffff0000, v250
	v_lshlrev_b32_e32 v16, 16, v251
	v_and_b32_e32 v17, 0xffff0000, v251
	v_pk_fma_f32 v[6:7], v[6:7], 0.5, v[20:21] op_sel_hi:[1,0,1]
	v_pk_fma_f32 v[8:9], v[8:9], 0.5, v[14:15] op_sel_hi:[1,0,1]
	v_pk_fma_f32 v[14:15], v[4:5], 0.5, v[16:17] op_sel_hi:[1,0,1]
	v_pk_fma_f32 v[16:17], v[2:3], 0.5, v[22:23] op_sel_hi:[1,0,1]
	v_mul_f32_e32 v2, v7, v7
	v_fmac_f32_e32 v2, v6, v6
	v_fmac_f32_e32 v2, v8, v8
	v_fmac_f32_e32 v2, v9, v9
	v_fmac_f32_e32 v2, v16, v16
	v_fmac_f32_e32 v2, v17, v17
	v_fmac_f32_e32 v2, v14, v14
	v_fmac_f32_e32 v2, v15, v15
	v_add_f32_e32 v2, v27, v2
	ds_bpermute_b32 v3, v122, v2
	v_cvt_pk_bf16_f32 v4, v6, v7
	v_cvt_pk_bf16_f32 v5, v8, v9
	v_cvt_pk_bf16_f32 v6, v16, v17
	v_cvt_pk_bf16_f32 v7, v14, v15
	s_waitcnt lgkmcnt(0)
	v_add_f32_e32 v2, v2, v3
	ds_bpermute_b32 v3, v116, v2
	global_store_dwordx4 v[24:25], v[4:7], off offset:256
	s_and_saveexec_b64 s[20:21], s[2:3]
	s_cbranch_execz .LBB0_1196
	v_lshl_add_u64 v[4:5], v[18:19], 2, s[12:13]
	s_waitcnt lgkmcnt(0)
	v_add_f32_e32 v2, v2, v3
	global_atomic_add_f32 v[4:5], v2, off

.LBB0_1465:
	v_lshl_add_u32 v148, s53, 8, v1
	v_ashrrev_i32_e32 v149, 31, v148
	v_lshl_or_b32 v146, s54, 8, v151
	v_lshlrev_b64 v[156:157], 11, v[148:149]
	v_ashrrev_i32_e32 v147, 31, v146
	v_lshl_add_u64 v[156:157], s[92:93], 0, v[156:157]
	v_lshl_add_u64 v[160:161], v[146:147], 1, v[156:157]
	global_load_dwordx4 v[170:173], v[160:161], off
	global_load_dwordx4 v[174:177], v[160:161], off offset:256
	v_or_b32_e32 v178, 16, v148
	v_ashrrev_i32_e32 v179, 31, v178
	v_lshlrev_b64 v[246:247], 11, v[178:179]
	v_lshl_add_u64 v[246:247], s[92:93], 0, v[246:247]
	v_lshl_add_u64 v[248:249], v[146:147], 1, v[246:247]
	global_load_dwordx4 v[182:185], v[248:249], off
	global_load_dwordx4 v[186:189], v[248:249], off offset:256
	v_or_b32_e32 v250, 32, v148
	v_ashrrev_i32_e32 v251, 31, v250
	v_lshlrev_b64 v[252:253], 11, v[250:251]
	v_lshl_add_u64 v[252:253], s[92:93], 0, v[252:253]
	v_lshl_add_u64 v[254:255], v[146:147], 1, v[252:253]
	global_load_dwordx4 v[190:193], v[254:255], off
	global_load_dwordx4 v[194:197], v[254:255], off offset:256
	v_or_b32_e32 v178, 48, v148
	v_ashrrev_i32_e32 v179, 31, v178
	v_lshlrev_b64 v[246:247], 11, v[178:179]
	v_lshl_add_u64 v[246:247], s[92:93], 0, v[246:247]
	v_lshl_add_u64 v[248:249], v[146:147], 1, v[246:247]
	global_load_dwordx4 v[198:201], v[248:249], off
	global_load_dwordx4 v[202:205], v[248:249], off offset:256
	v_add_u32_e32 v250, 0x80, v148
	v_ashrrev_i32_e32 v251, 31, v250
	v_lshlrev_b64 v[252:253], 11, v[250:251]
	v_lshl_add_u64 v[252:253], s[92:93], 0, v[252:253]
	v_lshl_add_u64 v[254:255], v[146:147], 1, v[252:253]
	global_load_dwordx4 v[206:209], v[254:255], off
	global_load_dwordx4 v[210:213], v[254:255], off offset:256
	v_add_u32_e32 v178, 0x90, v148
	v_ashrrev_i32_e32 v179, 31, v178
	v_lshlrev_b64 v[246:247], 11, v[178:179]
	v_lshl_add_u64 v[246:247], s[92:93], 0, v[246:247]
	v_lshl_add_u64 v[248:249], v[146:147], 1, v[246:247]
	global_load_dwordx4 v[214:217], v[248:249], off
	global_load_dwordx4 v[224:227], v[248:249], off offset:256
	v_add_u32_e32 v250, 0xa0, v148
	v_ashrrev_i32_e32 v251, 31, v250
	v_lshlrev_b64 v[252:253], 11, v[250:251]
	v_lshl_add_u64 v[252:253], s[92:93], 0, v[252:253]
	v_lshl_add_u64 v[254:255], v[146:147], 1, v[252:253]
	global_load_dwordx4 v[228:231], v[254:255], off
	global_load_dwordx4 v[232:235], v[254:255], off offset:256
	v_add_u32_e32 v178, 0xb0, v148
	v_ashrrev_i32_e32 v179, 31, v178
	v_lshlrev_b64 v[246:247], 11, v[178:179]
	v_lshl_add_u64 v[246:247], s[92:93], 0, v[246:247]
	v_lshl_add_u64 v[248:249], v[146:147], 1, v[246:247]
	global_load_dwordx4 v[236:239], v[248:249], off
	global_load_dwordx4 v[240:243], v[248:249], off offset:256
	s_nop 0
	v_xor_b32_e32 v168, 32, v155
	s_waitcnt vmcnt(15)
	v_lshlrev_b32_e32 v162, 16, v170
	v_and_b32_e32 v163, 0xffff0000, v170
	v_lshlrev_b32_e32 v156, 16, v171
	v_and_b32_e32 v157, 0xffff0000, v171
	v_lshlrev_b32_e32 v164, 16, v172
	v_and_b32_e32 v165, 0xffff0000, v172
	v_lshlrev_b32_e32 v158, 16, v173
	v_and_b32_e32 v159, 0xffff0000, v173
	v_pk_fma_f32 v[128:129], v[128:129], 0.5, v[156:157] op_sel_hi:[1,0,1]
	v_pk_fma_f32 v[162:163], v[126:127], 0.5, v[162:163] op_sel_hi:[1,0,1]
	v_pk_fma_f32 v[166:167], v[124:125], 0.5, v[158:159] op_sel_hi:[1,0,1]
	v_pk_fma_f32 v[164:165], v[122:123], 0.5, v[164:165] op_sel_hi:[1,0,1]
	v_cvt_pk_bf16_f32 v124, v162, v163
	v_cvt_pk_bf16_f32 v125, v128, v129
	v_mul_f32_e32 v169, v163, v163
	v_cvt_pk_bf16_f32 v126, v164, v165
	v_cvt_pk_bf16_f32 v127, v166, v167
	s_nop 0
	v_fmac_f32_e32 v169, v162, v162
	v_fmac_f32_e32 v169, v128, v128
	v_fmac_f32_e32 v169, v129, v129
	v_and_b32_e32 v123, 64, v155
	v_fmac_f32_e32 v169, v164, v164
	v_xor_b32_e32 v122, 16, v155
	v_add_u32_e32 v123, 64, v123
	v_fmac_f32_e32 v169, v165, v165
	v_cmp_lt_i32_e32 vcc, v122, v123
	v_fmac_f32_e32 v169, v166, v166
	v_fmac_f32_e32 v169, v167, v167
	v_cndmask_b32_e32 v122, v155, v122, vcc
	v_lshlrev_b32_e32 v122, 2, v122
	v_cmp_lt_i32_e32 vcc, v168, v123
	global_store_dwordx4 v[160:161], v[124:127], off
	s_waitcnt vmcnt(15)
	v_lshlrev_b32_e32 v128, 16, v174
	v_and_b32_e32 v129, 0xffff0000, v174
	v_lshlrev_b32_e32 v156, 16, v175
	v_and_b32_e32 v157, 0xffff0000, v175
	v_lshlrev_b32_e32 v162, 16, v176
	v_and_b32_e32 v163, 0xffff0000, v176
	v_pk_fma_f32 v[118:119], v[118:119], 0.5, v[128:129] op_sel_hi:[1,0,1]
	v_pk_fma_f32 v[120:121], v[120:121], 0.5, v[156:157] op_sel_hi:[1,0,1]
	v_pk_fma_f32 v[156:157], v[114:115], 0.5, v[162:163] op_sel_hi:[1,0,1]
	v_mul_f32_e32 v114, v119, v119
	v_fmac_f32_e32 v114, v118, v118
	v_fmac_f32_e32 v114, v120, v120
	v_fmac_f32_e32 v114, v121, v121
	v_lshlrev_b32_e32 v158, 16, v177
	v_and_b32_e32 v159, 0xffff0000, v177
	v_fmac_f32_e32 v114, v156, v156
	v_pk_fma_f32 v[128:129], v[116:117], 0.5, v[158:159] op_sel_hi:[1,0,1]
	v_fmac_f32_e32 v114, v157, v157
	v_fmac_f32_e32 v114, v128, v128
	v_fmac_f32_e32 v114, v129, v129
	v_add_f32_e32 v114, v169, v114
	ds_bpermute_b32 v115, v122, v114
	v_cndmask_b32_e32 v116, v155, v168, vcc
	v_lshlrev_b32_e32 v116, 2, v116
	v_cvt_pk_bf16_f32 v118, v118, v119
	v_cvt_pk_bf16_f32 v119, v120, v121
	s_waitcnt lgkmcnt(0)
	v_add_f32_e32 v114, v114, v115
	ds_bpermute_b32 v115, v116, v114
	v_cvt_pk_bf16_f32 v120, v156, v157
	v_cvt_pk_bf16_f32 v121, v128, v129
	global_store_dwordx4 v[160:161], v[118:121], off offset:256
	s_and_saveexec_b64 s[22:23], s[2:3]
	s_cbranch_execz .LBB0_1467
	v_lshl_add_u64 v[118:119], v[148:149], 2, s[14:15]
	s_waitcnt lgkmcnt(0)
	v_add_f32_e32 v114, v114, v115
	global_atomic_add_f32 v[118:119], v114, off
.LBB0_1467:
	s_or_b64 exec, exec, s[22:23]
	v_or_b32_e32 v114, 16, v148
	s_waitcnt lgkmcnt(0)
	v_ashrrev_i32_e32 v115, 31, v114
	v_lshlrev_b64 v[118:119], 11, v[114:115]
	v_lshl_add_u64 v[118:119], s[92:93], 0, v[118:119]
	v_lshl_add_u64 v[124:125], v[146:147], 1, v[118:119]
	s_nop 0
	s_waitcnt vmcnt(15)
	v_lshlrev_b32_e32 v126, 16, v182
	v_and_b32_e32 v127, 0xffff0000, v182
	v_lshlrev_b32_e32 v118, 16, v183
	v_and_b32_e32 v119, 0xffff0000, v183
	v_lshlrev_b32_e32 v128, 16, v184
	v_and_b32_e32 v129, 0xffff0000, v184
	v_lshlrev_b32_e32 v120, 16, v185
	v_and_b32_e32 v121, 0xffff0000, v185
	v_pk_fma_f32 v[118:119], v[112:113], 0.5, v[118:119] op_sel_hi:[1,0,1]
	v_pk_fma_f32 v[126:127], v[110:111], 0.5, v[126:127] op_sel_hi:[1,0,1]
	v_pk_fma_f32 v[120:121], v[108:109], 0.5, v[120:121] op_sel_hi:[1,0,1]
	v_pk_fma_f32 v[128:129], v[106:107], 0.5, v[128:129] op_sel_hi:[1,0,1]
	v_cvt_pk_bf16_f32 v106, v126, v127
	v_cvt_pk_bf16_f32 v107, v118, v119
	v_mul_f32_e32 v117, v127, v127
	v_cvt_pk_bf16_f32 v108, v128, v129
	v_cvt_pk_bf16_f32 v109, v120, v121
	s_nop 0
	v_fmac_f32_e32 v117, v126, v126
	v_fmac_f32_e32 v117, v118, v118
	v_fmac_f32_e32 v117, v119, v119
	v_fmac_f32_e32 v117, v128, v128
	v_fmac_f32_e32 v117, v129, v129
	v_fmac_f32_e32 v117, v120, v120
	v_fmac_f32_e32 v117, v121, v121
	global_store_dwordx4 v[124:125], v[106:109], off
	s_waitcnt vmcnt(15)
	v_lshlrev_b32_e32 v118, 16, v186
	v_and_b32_e32 v119, 0xffff0000, v186
	v_lshlrev_b32_e32 v110, 16, v187
	v_and_b32_e32 v111, 0xffff0000, v187
	v_lshlrev_b32_e32 v120, 16, v188
	v_and_b32_e32 v121, 0xffff0000, v188
	v_lshlrev_b32_e32 v112, 16, v189
	v_and_b32_e32 v113, 0xffff0000, v189
	v_pk_fma_f32 v[102:103], v[102:103], 0.5, v[118:119] op_sel_hi:[1,0,1]
	v_pk_fma_f32 v[104:105], v[104:105], 0.5, v[110:111] op_sel_hi:[1,0,1]
	v_pk_fma_f32 v[110:111], v[100:101], 0.5, v[112:113] op_sel_hi:[1,0,1]
	v_pk_fma_f32 v[112:113], v[98:99], 0.5, v[120:121] op_sel_hi:[1,0,1]
	v_mul_f32_e32 v98, v103, v103
	v_fmac_f32_e32 v98, v102, v102
	v_fmac_f32_e32 v98, v104, v104
	v_fmac_f32_e32 v98, v105, v105
	v_fmac_f32_e32 v98, v112, v112
	v_fmac_f32_e32 v98, v113, v113
	v_fmac_f32_e32 v98, v110, v110
	v_fmac_f32_e32 v98, v111, v111
	v_add_f32_e32 v98, v117, v98
	ds_bpermute_b32 v99, v122, v98
	v_cvt_pk_bf16_f32 v100, v102, v103
	v_cvt_pk_bf16_f32 v101, v104, v105
	v_cvt_pk_bf16_f32 v102, v112, v113
	v_cvt_pk_bf16_f32 v103, v110, v111
	s_waitcnt lgkmcnt(0)
	v_add_f32_e32 v98, v98, v99
	ds_bpermute_b32 v99, v116, v98
	global_store_dwordx4 v[124:125], v[100:103], off offset:256
	s_and_saveexec_b64 s[22:23], s[2:3]
	s_cbranch_execz .LBB0_1469
	v_lshl_add_u64 v[100:101], v[114:115], 2, s[14:15]
	s_waitcnt lgkmcnt(0)
	v_add_f32_e32 v98, v98, v99
	global_atomic_add_f32 v[100:101], v98, off
.LBB0_1469:
	s_or_b64 exec, exec, s[22:23]
	v_or_b32_e32 v98, 32, v148
	s_waitcnt lgkmcnt(0)
	v_ashrrev_i32_e32 v99, 31, v98
	v_lshlrev_b64 v[100:101], 11, v[98:99]
	v_lshl_add_u64 v[100:101], s[92:93], 0, v[100:101]
	v_lshl_add_u64 v[104:105], v[146:147], 1, v[100:101]
	s_nop 0
	s_waitcnt vmcnt(15)
	v_lshlrev_b32_e32 v106, 16, v190
	v_and_b32_e32 v107, 0xffff0000, v190
	v_lshlrev_b32_e32 v100, 16, v191
	v_and_b32_e32 v101, 0xffff0000, v191
	v_lshlrev_b32_e32 v108, 16, v192
	v_and_b32_e32 v109, 0xffff0000, v192
	v_lshlrev_b32_e32 v102, 16, v193
	v_and_b32_e32 v103, 0xffff0000, v193
	v_pk_fma_f32 v[100:101], v[96:97], 0.5, v[100:101] op_sel_hi:[1,0,1]
	v_pk_fma_f32 v[106:107], v[94:95], 0.5, v[106:107] op_sel_hi:[1,0,1]
	v_pk_fma_f32 v[102:103], v[92:93], 0.5, v[102:103] op_sel_hi:[1,0,1]
	v_pk_fma_f32 v[108:109], v[90:91], 0.5, v[108:109] op_sel_hi:[1,0,1]
	v_cvt_pk_bf16_f32 v90, v106, v107
	v_cvt_pk_bf16_f32 v91, v100, v101
	v_mul_f32_e32 v107, v107, v107
	v_cvt_pk_bf16_f32 v92, v108, v109
	v_cvt_pk_bf16_f32 v93, v102, v103
	s_nop 0
	v_fmac_f32_e32 v107, v106, v106
	v_fmac_f32_e32 v107, v100, v100
	v_fmac_f32_e32 v107, v101, v101
	v_fmac_f32_e32 v107, v108, v108
	v_fmac_f32_e32 v107, v109, v109
	v_fmac_f32_e32 v107, v102, v102
	v_fmac_f32_e32 v107, v103, v103
	global_store_dwordx4 v[104:105], v[90:93], off
	s_waitcnt vmcnt(15)
	v_lshlrev_b32_e32 v100, 16, v194
	v_and_b32_e32 v101, 0xffff0000, v194
	v_lshlrev_b32_e32 v94, 16, v195
	v_and_b32_e32 v95, 0xffff0000, v195
	v_lshlrev_b32_e32 v102, 16, v196
	v_and_b32_e32 v103, 0xffff0000, v196
	v_lshlrev_b32_e32 v96, 16, v197
	v_and_b32_e32 v97, 0xffff0000, v197
	v_pk_fma_f32 v[86:87], v[86:87], 0.5, v[100:101] op_sel_hi:[1,0,1]
	v_pk_fma_f32 v[88:89], v[88:89], 0.5, v[94:95] op_sel_hi:[1,0,1]
	v_pk_fma_f32 v[94:95], v[84:85], 0.5, v[96:97] op_sel_hi:[1,0,1]
	v_pk_fma_f32 v[96:97], v[82:83], 0.5, v[102:103] op_sel_hi:[1,0,1]
	v_mul_f32_e32 v82, v87, v87
	v_fmac_f32_e32 v82, v86, v86
	v_fmac_f32_e32 v82, v88, v88
	v_fmac_f32_e32 v82, v89, v89
	v_fmac_f32_e32 v82, v96, v96
	v_fmac_f32_e32 v82, v97, v97
	v_fmac_f32_e32 v82, v94, v94
	v_fmac_f32_e32 v82, v95, v95
	v_add_f32_e32 v82, v107, v82
	ds_bpermute_b32 v83, v122, v82
	v_cvt_pk_bf16_f32 v84, v86, v87
	v_cvt_pk_bf16_f32 v85, v88, v89
	v_cvt_pk_bf16_f32 v86, v96, v97
	v_cvt_pk_bf16_f32 v87, v94, v95
	s_waitcnt lgkmcnt(0)
	v_add_f32_e32 v82, v82, v83
	ds_bpermute_b32 v83, v116, v82
	global_store_dwordx4 v[104:105], v[84:87], off offset:256
	s_and_saveexec_b64 s[22:23], s[2:3]
	s_cbranch_execz .LBB0_1471
	v_lshl_add_u64 v[84:85], v[98:99], 2, s[14:15]
	s_waitcnt lgkmcnt(0)
	v_add_f32_e32 v82, v82, v83
	global_atomic_add_f32 v[84:85], v82, off
.LBB0_1471:
	s_or_b64 exec, exec, s[22:23]
	v_or_b32_e32 v82, 48, v148
	s_waitcnt lgkmcnt(0)
	v_ashrrev_i32_e32 v83, 31, v82
	v_lshlrev_b64 v[84:85], 11, v[82:83]
	v_lshl_add_u64 v[84:85], s[92:93], 0, v[84:85]
	v_lshl_add_u64 v[88:89], v[146:147], 1, v[84:85]
	s_nop 0
	s_waitcnt vmcnt(15)
	v_lshlrev_b32_e32 v90, 16, v198
	v_and_b32_e32 v91, 0xffff0000, v198
	v_lshlrev_b32_e32 v84, 16, v199
	v_and_b32_e32 v85, 0xffff0000, v199
	v_lshlrev_b32_e32 v92, 16, v200
	v_and_b32_e32 v93, 0xffff0000, v200
	v_lshlrev_b32_e32 v86, 16, v201
	v_and_b32_e32 v87, 0xffff0000, v201
	v_pk_fma_f32 v[84:85], v[80:81], 0.5, v[84:85] op_sel_hi:[1,0,1]
	v_pk_fma_f32 v[90:91], v[78:79], 0.5, v[90:91] op_sel_hi:[1,0,1]
	v_pk_fma_f32 v[86:87], v[76:77], 0.5, v[86:87] op_sel_hi:[1,0,1]
	v_pk_fma_f32 v[92:93], v[74:75], 0.5, v[92:93] op_sel_hi:[1,0,1]
	v_cvt_pk_bf16_f32 v74, v90, v91
	v_cvt_pk_bf16_f32 v75, v84, v85
	v_mul_f32_e32 v91, v91, v91
	v_cvt_pk_bf16_f32 v76, v92, v93
	v_cvt_pk_bf16_f32 v77, v86, v87
	s_nop 0
	v_fmac_f32_e32 v91, v90, v90
	v_fmac_f32_e32 v91, v84, v84
	v_fmac_f32_e32 v91, v85, v85
	v_fmac_f32_e32 v91, v92, v92
	v_fmac_f32_e32 v91, v93, v93
	v_fmac_f32_e32 v91, v86, v86
	v_fmac_f32_e32 v91, v87, v87
	global_store_dwordx4 v[88:89], v[74:77], off
	s_waitcnt vmcnt(15)
	v_lshlrev_b32_e32 v84, 16, v202
	v_and_b32_e32 v85, 0xffff0000, v202
	v_lshlrev_b32_e32 v78, 16, v203
	v_and_b32_e32 v79, 0xffff0000, v203
	v_lshlrev_b32_e32 v86, 16, v204
	v_and_b32_e32 v87, 0xffff0000, v204
	v_lshlrev_b32_e32 v80, 16, v205
	v_and_b32_e32 v81, 0xffff0000, v205
	v_pk_fma_f32 v[70:71], v[70:71], 0.5, v[84:85] op_sel_hi:[1,0,1]
	v_pk_fma_f32 v[72:73], v[72:73], 0.5, v[78:79] op_sel_hi:[1,0,1]
	v_pk_fma_f32 v[78:79], v[68:69], 0.5, v[80:81] op_sel_hi:[1,0,1]
	v_pk_fma_f32 v[80:81], v[66:67], 0.5, v[86:87] op_sel_hi:[1,0,1]
	v_mul_f32_e32 v66, v71, v71
	v_fmac_f32_e32 v66, v70, v70
	v_fmac_f32_e32 v66, v72, v72
	v_fmac_f32_e32 v66, v73, v73
	v_fmac_f32_e32 v66, v80, v80
	v_fmac_f32_e32 v66, v81, v81
	v_fmac_f32_e32 v66, v78, v78
	v_fmac_f32_e32 v66, v79, v79
	v_add_f32_e32 v66, v91, v66
	ds_bpermute_b32 v67, v122, v66
	v_cvt_pk_bf16_f32 v68, v70, v71
	v_cvt_pk_bf16_f32 v69, v72, v73
	v_cvt_pk_bf16_f32 v70, v80, v81
	v_cvt_pk_bf16_f32 v71, v78, v79
	s_waitcnt lgkmcnt(0)
	v_add_f32_e32 v66, v66, v67
	ds_bpermute_b32 v67, v116, v66
	global_store_dwordx4 v[88:89], v[68:71], off offset:256
	s_and_saveexec_b64 s[22:23], s[2:3]
	s_cbranch_execz .LBB0_1473
	v_lshl_add_u64 v[68:69], v[82:83], 2, s[14:15]
	s_waitcnt lgkmcnt(0)
	v_add_f32_e32 v66, v66, v67
	global_atomic_add_f32 v[68:69], v66, off
.LBB0_1473:
	s_or_b64 exec, exec, s[22:23]
	v_add_u32_e32 v66, 0x80, v148
	s_waitcnt lgkmcnt(0)
	v_ashrrev_i32_e32 v67, 31, v66
	v_lshlrev_b64 v[68:69], 11, v[66:67]
	v_lshl_add_u64 v[68:69], s[92:93], 0, v[68:69]
	v_lshl_add_u64 v[72:73], v[146:147], 1, v[68:69]
	s_nop 0
	s_waitcnt vmcnt(15)
	v_lshlrev_b32_e32 v74, 16, v206
	v_and_b32_e32 v75, 0xffff0000, v206
	v_lshlrev_b32_e32 v68, 16, v207
	v_and_b32_e32 v69, 0xffff0000, v207
	v_lshlrev_b32_e32 v76, 16, v208
	v_and_b32_e32 v77, 0xffff0000, v208
	v_lshlrev_b32_e32 v70, 16, v209
	v_and_b32_e32 v71, 0xffff0000, v209
	v_pk_fma_f32 v[68:69], v[64:65], 0.5, v[68:69] op_sel_hi:[1,0,1]
	v_pk_fma_f32 v[74:75], v[62:63], 0.5, v[74:75] op_sel_hi:[1,0,1]
	v_pk_fma_f32 v[70:71], v[60:61], 0.5, v[70:71] op_sel_hi:[1,0,1]
	v_pk_fma_f32 v[76:77], v[58:59], 0.5, v[76:77] op_sel_hi:[1,0,1]
	v_cvt_pk_bf16_f32 v58, v74, v75
	v_cvt_pk_bf16_f32 v59, v68, v69
	v_mul_f32_e32 v75, v75, v75
	v_cvt_pk_bf16_f32 v60, v76, v77
	v_cvt_pk_bf16_f32 v61, v70, v71
	s_nop 0
	v_fmac_f32_e32 v75, v74, v74
	v_fmac_f32_e32 v75, v68, v68
	v_fmac_f32_e32 v75, v69, v69
	v_fmac_f32_e32 v75, v76, v76
	v_fmac_f32_e32 v75, v77, v77
	v_fmac_f32_e32 v75, v70, v70
	v_fmac_f32_e32 v75, v71, v71
	global_store_dwordx4 v[72:73], v[58:61], off
	s_waitcnt vmcnt(15)
	v_lshlrev_b32_e32 v68, 16, v210
	v_and_b32_e32 v69, 0xffff0000, v210
	v_lshlrev_b32_e32 v62, 16, v211
	v_and_b32_e32 v63, 0xffff0000, v211
	v_lshlrev_b32_e32 v70, 16, v212
	v_and_b32_e32 v71, 0xffff0000, v212
	v_lshlrev_b32_e32 v64, 16, v213
	v_and_b32_e32 v65, 0xffff0000, v213
	v_pk_fma_f32 v[54:55], v[54:55], 0.5, v[68:69] op_sel_hi:[1,0,1]
	v_pk_fma_f32 v[56:57], v[56:57], 0.5, v[62:63] op_sel_hi:[1,0,1]
	v_pk_fma_f32 v[62:63], v[52:53], 0.5, v[64:65] op_sel_hi:[1,0,1]
	v_pk_fma_f32 v[64:65], v[50:51], 0.5, v[70:71] op_sel_hi:[1,0,1]
	v_mul_f32_e32 v50, v55, v55
	v_fmac_f32_e32 v50, v54, v54
	v_fmac_f32_e32 v50, v56, v56
	v_fmac_f32_e32 v50, v57, v57
	v_fmac_f32_e32 v50, v64, v64
	v_fmac_f32_e32 v50, v65, v65
	v_fmac_f32_e32 v50, v62, v62
	v_fmac_f32_e32 v50, v63, v63
	v_add_f32_e32 v50, v75, v50
	ds_bpermute_b32 v51, v122, v50
	v_cvt_pk_bf16_f32 v52, v54, v55
	v_cvt_pk_bf16_f32 v53, v56, v57
	v_cvt_pk_bf16_f32 v54, v64, v65
	v_cvt_pk_bf16_f32 v55, v62, v63
	s_waitcnt lgkmcnt(0)
	v_add_f32_e32 v50, v50, v51
	ds_bpermute_b32 v51, v116, v50
	global_store_dwordx4 v[72:73], v[52:55], off offset:256
	s_and_saveexec_b64 s[22:23], s[2:3]
	s_cbranch_execz .LBB0_1475
	v_lshl_add_u64 v[52:53], v[66:67], 2, s[14:15]
	s_waitcnt lgkmcnt(0)
	v_add_f32_e32 v50, v50, v51
	global_atomic_add_f32 v[52:53], v50, off
.LBB0_1475:
	s_or_b64 exec, exec, s[22:23]
	v_add_u32_e32 v50, 0x90, v148
	s_waitcnt lgkmcnt(0)
	v_ashrrev_i32_e32 v51, 31, v50
	v_lshlrev_b64 v[52:53], 11, v[50:51]
	v_lshl_add_u64 v[52:53], s[92:93], 0, v[52:53]
	v_lshl_add_u64 v[56:57], v[146:147], 1, v[52:53]
	s_nop 0
	s_waitcnt vmcnt(15)
	v_lshlrev_b32_e32 v58, 16, v214
	v_and_b32_e32 v59, 0xffff0000, v214
	v_lshlrev_b32_e32 v52, 16, v215
	v_and_b32_e32 v53, 0xffff0000, v215
	v_lshlrev_b32_e32 v60, 16, v216
	v_and_b32_e32 v61, 0xffff0000, v216
	v_lshlrev_b32_e32 v54, 16, v217
	v_and_b32_e32 v55, 0xffff0000, v217
	v_pk_fma_f32 v[52:53], v[48:49], 0.5, v[52:53] op_sel_hi:[1,0,1]
	v_pk_fma_f32 v[58:59], v[46:47], 0.5, v[58:59] op_sel_hi:[1,0,1]
	v_pk_fma_f32 v[54:55], v[44:45], 0.5, v[54:55] op_sel_hi:[1,0,1]
	v_pk_fma_f32 v[60:61], v[42:43], 0.5, v[60:61] op_sel_hi:[1,0,1]
	v_cvt_pk_bf16_f32 v42, v58, v59
	v_cvt_pk_bf16_f32 v43, v52, v53
	v_mul_f32_e32 v59, v59, v59
	v_cvt_pk_bf16_f32 v44, v60, v61
	v_cvt_pk_bf16_f32 v45, v54, v55
	s_nop 0
	v_fmac_f32_e32 v59, v58, v58
	v_fmac_f32_e32 v59, v52, v52
	v_fmac_f32_e32 v59, v53, v53
	v_fmac_f32_e32 v59, v60, v60
	v_fmac_f32_e32 v59, v61, v61
	v_fmac_f32_e32 v59, v54, v54
	v_fmac_f32_e32 v59, v55, v55
	global_store_dwordx4 v[56:57], v[42:45], off
	s_waitcnt vmcnt(15)
	v_lshlrev_b32_e32 v52, 16, v224
	v_and_b32_e32 v53, 0xffff0000, v224
	v_lshlrev_b32_e32 v46, 16, v225
	v_and_b32_e32 v47, 0xffff0000, v225
	v_lshlrev_b32_e32 v54, 16, v226
	v_and_b32_e32 v55, 0xffff0000, v226
	v_lshlrev_b32_e32 v48, 16, v227
	v_and_b32_e32 v49, 0xffff0000, v227
	v_pk_fma_f32 v[38:39], v[38:39], 0.5, v[52:53] op_sel_hi:[1,0,1]
	v_pk_fma_f32 v[40:41], v[40:41], 0.5, v[46:47] op_sel_hi:[1,0,1]
	v_pk_fma_f32 v[46:47], v[36:37], 0.5, v[48:49] op_sel_hi:[1,0,1]
	v_pk_fma_f32 v[48:49], v[34:35], 0.5, v[54:55] op_sel_hi:[1,0,1]
	v_mul_f32_e32 v34, v39, v39
	v_fmac_f32_e32 v34, v38, v38
	v_fmac_f32_e32 v34, v40, v40
	v_fmac_f32_e32 v34, v41, v41
	v_fmac_f32_e32 v34, v48, v48
	v_fmac_f32_e32 v34, v49, v49
	v_fmac_f32_e32 v34, v46, v46
	v_fmac_f32_e32 v34, v47, v47
	v_add_f32_e32 v34, v59, v34
	ds_bpermute_b32 v35, v122, v34
	v_cvt_pk_bf16_f32 v36, v38, v39
	v_cvt_pk_bf16_f32 v37, v40, v41
	v_cvt_pk_bf16_f32 v38, v48, v49
	v_cvt_pk_bf16_f32 v39, v46, v47
	s_waitcnt lgkmcnt(0)
	v_add_f32_e32 v34, v34, v35
	ds_bpermute_b32 v35, v116, v34
	global_store_dwordx4 v[56:57], v[36:39], off offset:256
	s_and_saveexec_b64 s[22:23], s[2:3]
	s_cbranch_execz .LBB0_1477
	v_lshl_add_u64 v[36:37], v[50:51], 2, s[14:15]
	s_waitcnt lgkmcnt(0)
	v_add_f32_e32 v34, v34, v35
	global_atomic_add_f32 v[36:37], v34, off
.LBB0_1477:
	s_or_b64 exec, exec, s[22:23]
	v_add_u32_e32 v34, 0xa0, v148
	s_waitcnt lgkmcnt(0)
	v_ashrrev_i32_e32 v35, 31, v34
	v_lshlrev_b64 v[36:37], 11, v[34:35]
	v_lshl_add_u64 v[36:37], s[92:93], 0, v[36:37]
	v_lshl_add_u64 v[40:41], v[146:147], 1, v[36:37]
	s_nop 0
	s_waitcnt vmcnt(15)
	v_lshlrev_b32_e32 v42, 16, v228
	v_and_b32_e32 v43, 0xffff0000, v228
	v_lshlrev_b32_e32 v36, 16, v229
	v_and_b32_e32 v37, 0xffff0000, v229
	v_lshlrev_b32_e32 v44, 16, v230
	v_and_b32_e32 v45, 0xffff0000, v230
	v_lshlrev_b32_e32 v38, 16, v231
	v_and_b32_e32 v39, 0xffff0000, v231
	v_pk_fma_f32 v[36:37], v[32:33], 0.5, v[36:37] op_sel_hi:[1,0,1]
	v_pk_fma_f32 v[42:43], v[30:31], 0.5, v[42:43] op_sel_hi:[1,0,1]
	v_pk_fma_f32 v[38:39], v[28:29], 0.5, v[38:39] op_sel_hi:[1,0,1]
	v_pk_fma_f32 v[44:45], v[26:27], 0.5, v[44:45] op_sel_hi:[1,0,1]
	v_cvt_pk_bf16_f32 v26, v42, v43
	v_cvt_pk_bf16_f32 v27, v36, v37
	v_mul_f32_e32 v43, v43, v43
	v_cvt_pk_bf16_f32 v28, v44, v45
	v_cvt_pk_bf16_f32 v29, v38, v39
	s_nop 0
	v_fmac_f32_e32 v43, v42, v42
	v_fmac_f32_e32 v43, v36, v36
	v_fmac_f32_e32 v43, v37, v37
	v_fmac_f32_e32 v43, v44, v44
	v_fmac_f32_e32 v43, v45, v45
	v_fmac_f32_e32 v43, v38, v38
	v_fmac_f32_e32 v43, v39, v39
	global_store_dwordx4 v[40:41], v[26:29], off
	s_waitcnt vmcnt(15)
	v_lshlrev_b32_e32 v36, 16, v232
	v_and_b32_e32 v37, 0xffff0000, v232
	v_lshlrev_b32_e32 v30, 16, v233
	v_and_b32_e32 v31, 0xffff0000, v233
	v_lshlrev_b32_e32 v38, 16, v234
	v_and_b32_e32 v39, 0xffff0000, v234
	v_lshlrev_b32_e32 v32, 16, v235
	v_and_b32_e32 v33, 0xffff0000, v235
	v_pk_fma_f32 v[22:23], v[22:23], 0.5, v[36:37] op_sel_hi:[1,0,1]
	v_pk_fma_f32 v[24:25], v[24:25], 0.5, v[30:31] op_sel_hi:[1,0,1]
	v_pk_fma_f32 v[30:31], v[20:21], 0.5, v[32:33] op_sel_hi:[1,0,1]
	v_pk_fma_f32 v[32:33], v[18:19], 0.5, v[38:39] op_sel_hi:[1,0,1]
	v_mul_f32_e32 v18, v23, v23
	v_fmac_f32_e32 v18, v22, v22
	v_fmac_f32_e32 v18, v24, v24
	v_fmac_f32_e32 v18, v25, v25
	v_fmac_f32_e32 v18, v32, v32
	v_fmac_f32_e32 v18, v33, v33
	v_fmac_f32_e32 v18, v30, v30
	v_fmac_f32_e32 v18, v31, v31
	v_add_f32_e32 v18, v43, v18
	ds_bpermute_b32 v19, v122, v18
	v_cvt_pk_bf16_f32 v20, v22, v23
	v_cvt_pk_bf16_f32 v21, v24, v25
	v_cvt_pk_bf16_f32 v22, v32, v33
	v_cvt_pk_bf16_f32 v23, v30, v31
	s_waitcnt lgkmcnt(0)
	v_add_f32_e32 v18, v18, v19
	ds_bpermute_b32 v19, v116, v18
	global_store_dwordx4 v[40:41], v[20:23], off offset:256
	s_and_saveexec_b64 s[22:23], s[2:3]
	s_cbranch_execz .LBB0_1479
	v_lshl_add_u64 v[20:21], v[34:35], 2, s[14:15]
	s_waitcnt lgkmcnt(0)
	v_add_f32_e32 v18, v18, v19
	global_atomic_add_f32 v[20:21], v18, off
.LBB0_1479:
	s_or_b64 exec, exec, s[22:23]
	v_add_u32_e32 v18, 0xb0, v148
	s_waitcnt lgkmcnt(0)
	v_ashrrev_i32_e32 v19, 31, v18
	v_lshlrev_b64 v[20:21], 11, v[18:19]
	v_lshl_add_u64 v[20:21], s[92:93], 0, v[20:21]
	v_lshl_add_u64 v[24:25], v[146:147], 1, v[20:21]
	s_nop 0
	s_waitcnt vmcnt(15)
	v_lshlrev_b32_e32 v26, 16, v236
	v_and_b32_e32 v27, 0xffff0000, v236
	v_lshlrev_b32_e32 v20, 16, v237
	v_and_b32_e32 v21, 0xffff0000, v237
	v_lshlrev_b32_e32 v28, 16, v238
	v_and_b32_e32 v29, 0xffff0000, v238
	v_lshlrev_b32_e32 v22, 16, v239
	v_and_b32_e32 v23, 0xffff0000, v239
	v_pk_fma_f32 v[20:21], v[16:17], 0.5, v[20:21] op_sel_hi:[1,0,1]
	v_pk_fma_f32 v[26:27], v[14:15], 0.5, v[26:27] op_sel_hi:[1,0,1]
	v_pk_fma_f32 v[22:23], v[12:13], 0.5, v[22:23] op_sel_hi:[1,0,1]
	v_pk_fma_f32 v[28:29], v[10:11], 0.5, v[28:29] op_sel_hi:[1,0,1]
	v_cvt_pk_bf16_f32 v10, v26, v27
	v_cvt_pk_bf16_f32 v11, v20, v21
	v_mul_f32_e32 v27, v27, v27
	v_cvt_pk_bf16_f32 v12, v28, v29
	v_cvt_pk_bf16_f32 v13, v22, v23
	s_nop 0
	v_fmac_f32_e32 v27, v26, v26
	v_fmac_f32_e32 v27, v20, v20
	v_fmac_f32_e32 v27, v21, v21
	v_fmac_f32_e32 v27, v28, v28
	v_fmac_f32_e32 v27, v29, v29
	v_fmac_f32_e32 v27, v22, v22
	v_fmac_f32_e32 v27, v23, v23
	global_store_dwordx4 v[24:25], v[10:13], off
	s_waitcnt vmcnt(15)
	v_lshlrev_b32_e32 v20, 16, v240
	v_and_b32_e32 v21, 0xffff0000, v240
	v_lshlrev_b32_e32 v14, 16, v241
	v_and_b32_e32 v15, 0xffff0000, v241
	v_lshlrev_b32_e32 v22, 16, v242
	v_and_b32_e32 v23, 0xffff0000, v242
	v_lshlrev_b32_e32 v16, 16, v243
	v_and_b32_e32 v17, 0xffff0000, v243
	v_pk_fma_f32 v[6:7], v[6:7], 0.5, v[20:21] op_sel_hi:[1,0,1]
	v_pk_fma_f32 v[8:9], v[8:9], 0.5, v[14:15] op_sel_hi:[1,0,1]
	v_pk_fma_f32 v[14:15], v[4:5], 0.5, v[16:17] op_sel_hi:[1,0,1]
	v_pk_fma_f32 v[16:17], v[2:3], 0.5, v[22:23] op_sel_hi:[1,0,1]
	v_mul_f32_e32 v2, v7, v7
	v_fmac_f32_e32 v2, v6, v6
	v_fmac_f32_e32 v2, v8, v8
	v_fmac_f32_e32 v2, v9, v9
	v_fmac_f32_e32 v2, v16, v16
	v_fmac_f32_e32 v2, v17, v17
	v_fmac_f32_e32 v2, v14, v14
	v_fmac_f32_e32 v2, v15, v15
	v_add_f32_e32 v2, v27, v2
	ds_bpermute_b32 v3, v122, v2
	v_cvt_pk_bf16_f32 v4, v6, v7
	v_cvt_pk_bf16_f32 v5, v8, v9
	v_cvt_pk_bf16_f32 v6, v16, v17
	v_cvt_pk_bf16_f32 v7, v14, v15
	s_waitcnt lgkmcnt(0)
	v_add_f32_e32 v2, v2, v3
	ds_bpermute_b32 v3, v116, v2
	global_store_dwordx4 v[24:25], v[4:7], off offset:256
	s_and_saveexec_b64 s[22:23], s[2:3]
	s_cbranch_execz .LBB0_1481
	v_lshl_add_u64 v[4:5], v[18:19], 2, s[14:15]
	s_waitcnt lgkmcnt(0)
	v_add_f32_e32 v2, v2, v3
	global_atomic_add_f32 v[4:5], v2, off

.LBB0_2040:
	v_lshl_add_u32 v146, s38, 8, v150
	v_lshl_or_b32 v144, s39, 8, v152
	v_ashrrev_i32_e32 v147, 31, v146
	v_ashrrev_i32_e32 v145, 31, v144
	v_lshlrev_b64 v[148:149], 11, v[146:147]
	v_lshl_add_u64 v[156:157], s[92:93], 0, v[148:149]
	v_lshlrev_b64 v[148:149], 1, v[144:145]
	v_lshl_add_u64 v[160:161], v[156:157], 0, v[148:149]
	global_load_dwordx4 v[168:171], v[160:161], off
	global_load_dwordx4 v[172:175], v[160:161], off offset:256
	v_or_b32_e32 v236, 16, v146
	v_ashrrev_i32_e32 v237, 31, v236
	v_lshlrev_b64 v[238:239], 11, v[236:237]
	v_lshl_add_u64 v[238:239], s[92:93], 0, v[238:239]
	v_lshl_add_u64 v[238:239], v[238:239], 0, v[148:149]
	global_load_dwordx4 v[176:179], v[238:239], off
	global_load_dwordx4 v[180:183], v[238:239], off offset:256
	v_or_b32_e32 v240, 32, v146
	v_ashrrev_i32_e32 v241, 31, v240
	v_lshlrev_b64 v[242:243], 11, v[240:241]
	v_lshl_add_u64 v[242:243], s[92:93], 0, v[242:243]
	v_lshl_add_u64 v[242:243], v[242:243], 0, v[148:149]
	global_load_dwordx4 v[184:187], v[242:243], off
	global_load_dwordx4 v[188:191], v[242:243], off offset:256
	v_or_b32_e32 v246, 48, v146
	v_ashrrev_i32_e32 v247, 31, v246
	v_lshlrev_b64 v[252:253], 11, v[246:247]
	v_lshl_add_u64 v[252:253], s[92:93], 0, v[252:253]
	v_lshl_add_u64 v[252:253], v[252:253], 0, v[148:149]
	global_load_dwordx4 v[192:195], v[252:253], off
	global_load_dwordx4 v[196:199], v[252:253], off offset:256
	v_add_u32_e32 v254, 0x80, v146
	v_ashrrev_i32_e32 v255, 31, v254
	v_lshlrev_b64 v[236:237], 11, v[254:255]
	v_lshl_add_u64 v[236:237], s[92:93], 0, v[236:237]
	v_lshl_add_u64 v[236:237], v[236:237], 0, v[148:149]
	global_load_dwordx4 v[200:203], v[236:237], off
	global_load_dwordx4 v[204:207], v[236:237], off offset:256
	v_add_u32_e32 v238, 0x90, v146
	v_ashrrev_i32_e32 v239, 31, v238
	v_lshlrev_b64 v[240:241], 11, v[238:239]
	v_lshl_add_u64 v[240:241], s[92:93], 0, v[240:241]
	v_lshl_add_u64 v[240:241], v[240:241], 0, v[148:149]
	global_load_dwordx4 v[208:211], v[240:241], off
	global_load_dwordx4 v[212:215], v[240:241], off offset:256
	v_add_u32_e32 v242, 0xa0, v146
	v_ashrrev_i32_e32 v243, 31, v242
	v_lshlrev_b64 v[246:247], 11, v[242:243]
	v_lshl_add_u64 v[246:247], s[92:93], 0, v[246:247]
	v_lshl_add_u64 v[246:247], v[246:247], 0, v[148:149]
	global_load_dwordx4 v[220:223], v[246:247], off
	global_load_dwordx4 v[224:227], v[246:247], off offset:256
	v_add_u32_e32 v252, 0xb0, v146
	v_ashrrev_i32_e32 v253, 31, v252
	v_lshlrev_b64 v[254:255], 11, v[252:253]
	v_lshl_add_u64 v[254:255], s[92:93], 0, v[254:255]
	v_lshl_add_u64 v[254:255], v[254:255], 0, v[148:149]
	global_load_dwordx4 v[228:231], v[254:255], off
	global_load_dwordx4 v[232:235], v[254:255], off offset:256
	s_nop 0
	v_lshlrev_b64 v[162:163], 12, v[146:147]
	v_lshlrev_b64 v[144:145], 2, v[144:145]
	v_lshl_add_u64 v[162:163], s[48:49], 0, v[162:163]
	v_lshl_add_u64 v[162:163], v[162:163], 0, v[144:145]
	s_and_b64 vcc, exec, s[0:1]
	s_mov_b64 s[0:1], -1
	s_waitcnt vmcnt(15)
	v_lshlrev_b32_e32 v164, 16, v168
	v_and_b32_e32 v165, 0xffff0000, v168
	v_lshlrev_b32_e32 v156, 16, v169
	v_and_b32_e32 v157, 0xffff0000, v169
	v_lshlrev_b32_e32 v166, 16, v170
	v_and_b32_e32 v167, 0xffff0000, v170
	v_lshlrev_b32_e32 v158, 16, v171
	v_and_b32_e32 v159, 0xffff0000, v171
	v_pk_fma_f32 v[126:127], v[126:127], 0.5, v[156:157] op_sel_hi:[1,0,1]
	v_pk_fma_f32 v[124:125], v[124:125], 0.5, v[164:165] op_sel_hi:[1,0,1]
	v_pk_fma_f32 v[122:123], v[122:123], 0.5, v[158:159] op_sel_hi:[1,0,1]
	v_pk_fma_f32 v[120:121], v[120:121], 0.5, v[166:167] op_sel_hi:[1,0,1]
	global_store_dwordx4 v[162:163], v[124:127], off nt
	global_store_dwordx4 v[162:163], v[120:123], off offset:16 nt
	s_nop 0
	v_or_b32_e32 v124, 16, v146
	v_ashrrev_i32_e32 v125, 31, v124
	v_lshlrev_b64 v[126:127], 11, v[124:125]
	v_lshl_add_u64 v[126:127], s[92:93], 0, v[126:127]
	v_lshl_add_u64 v[126:127], v[126:127], 0, v[148:149]
	s_waitcnt vmcnt(16)
	v_lshlrev_b32_e32 v156, 16, v172
	v_and_b32_e32 v157, 0xffff0000, v172
	v_lshlrev_b32_e32 v120, 16, v173
	v_and_b32_e32 v121, 0xffff0000, v173
	v_lshlrev_b32_e32 v158, 16, v174
	v_and_b32_e32 v159, 0xffff0000, v174
	v_lshlrev_b32_e32 v122, 16, v175
	v_and_b32_e32 v123, 0xffff0000, v175
	v_pk_fma_f32 v[118:119], v[118:119], 0.5, v[120:121] op_sel_hi:[1,0,1]
	v_pk_fma_f32 v[116:117], v[116:117], 0.5, v[156:157] op_sel_hi:[1,0,1]
	v_pk_fma_f32 v[114:115], v[114:115], 0.5, v[122:123] op_sel_hi:[1,0,1]
	v_pk_fma_f32 v[112:113], v[112:113], 0.5, v[158:159] op_sel_hi:[1,0,1]
	global_store_dwordx4 v[162:163], v[116:119], off offset:512 nt
	global_store_dwordx4 v[162:163], v[112:115], off offset:528 nt
	s_nop 0
	v_lshlrev_b64 v[116:117], 12, v[124:125]
	v_lshl_add_u64 v[116:117], s[48:49], 0, v[116:117]
	v_lshl_add_u64 v[116:117], v[116:117], 0, v[144:145]
	s_waitcnt vmcnt(17)
	v_lshlrev_b32_e32 v118, 16, v176
	v_and_b32_e32 v119, 0xffff0000, v176
	v_lshlrev_b32_e32 v112, 16, v177
	v_and_b32_e32 v113, 0xffff0000, v177
	v_lshlrev_b32_e32 v120, 16, v178
	v_and_b32_e32 v121, 0xffff0000, v178
	v_lshlrev_b32_e32 v114, 16, v179
	v_and_b32_e32 v115, 0xffff0000, v179
	v_pk_fma_f32 v[110:111], v[110:111], 0.5, v[112:113] op_sel_hi:[1,0,1]
	v_pk_fma_f32 v[108:109], v[108:109], 0.5, v[118:119] op_sel_hi:[1,0,1]
	v_pk_fma_f32 v[106:107], v[106:107], 0.5, v[114:115] op_sel_hi:[1,0,1]
	v_pk_fma_f32 v[104:105], v[104:105], 0.5, v[120:121] op_sel_hi:[1,0,1]
	global_store_dwordx4 v[116:117], v[108:111], off nt
	global_store_dwordx4 v[116:117], v[104:107], off offset:16 nt
	s_nop 0
	v_or_b32_e32 v108, 32, v146
	v_ashrrev_i32_e32 v109, 31, v108
	v_lshlrev_b64 v[110:111], 11, v[108:109]
	v_lshl_add_u64 v[110:111], s[92:93], 0, v[110:111]
	v_lshl_add_u64 v[110:111], v[110:111], 0, v[148:149]
	s_waitcnt vmcnt(18)
	v_lshlrev_b32_e32 v112, 16, v180
	v_and_b32_e32 v113, 0xffff0000, v180
	v_lshlrev_b32_e32 v104, 16, v181
	v_and_b32_e32 v105, 0xffff0000, v181
	v_lshlrev_b32_e32 v114, 16, v182
	v_and_b32_e32 v115, 0xffff0000, v182
	v_lshlrev_b32_e32 v106, 16, v183
	v_and_b32_e32 v107, 0xffff0000, v183
	v_pk_fma_f32 v[102:103], v[102:103], 0.5, v[104:105] op_sel_hi:[1,0,1]
	v_pk_fma_f32 v[100:101], v[100:101], 0.5, v[112:113] op_sel_hi:[1,0,1]
	v_pk_fma_f32 v[98:99], v[98:99], 0.5, v[106:107] op_sel_hi:[1,0,1]
	v_pk_fma_f32 v[96:97], v[96:97], 0.5, v[114:115] op_sel_hi:[1,0,1]
	global_store_dwordx4 v[116:117], v[100:103], off offset:512 nt
	global_store_dwordx4 v[116:117], v[96:99], off offset:528 nt
	s_nop 0
	v_lshlrev_b64 v[100:101], 12, v[108:109]
	v_lshl_add_u64 v[100:101], s[48:49], 0, v[100:101]
	v_lshl_add_u64 v[100:101], v[100:101], 0, v[144:145]
	s_waitcnt vmcnt(19)
	v_lshlrev_b32_e32 v102, 16, v184
	v_and_b32_e32 v103, 0xffff0000, v184
	v_lshlrev_b32_e32 v96, 16, v185
	v_and_b32_e32 v97, 0xffff0000, v185
	v_lshlrev_b32_e32 v104, 16, v186
	v_and_b32_e32 v105, 0xffff0000, v186
	v_lshlrev_b32_e32 v98, 16, v187
	v_and_b32_e32 v99, 0xffff0000, v187
	v_pk_fma_f32 v[94:95], v[94:95], 0.5, v[96:97] op_sel_hi:[1,0,1]
	v_pk_fma_f32 v[92:93], v[92:93], 0.5, v[102:103] op_sel_hi:[1,0,1]
	v_pk_fma_f32 v[90:91], v[90:91], 0.5, v[98:99] op_sel_hi:[1,0,1]
	v_pk_fma_f32 v[88:89], v[88:89], 0.5, v[104:105] op_sel_hi:[1,0,1]
	global_store_dwordx4 v[100:101], v[92:95], off nt
	global_store_dwordx4 v[100:101], v[88:91], off offset:16 nt
	s_nop 0
	v_or_b32_e32 v92, 48, v146
	v_ashrrev_i32_e32 v93, 31, v92
	v_lshlrev_b64 v[94:95], 11, v[92:93]
	v_lshl_add_u64 v[94:95], s[92:93], 0, v[94:95]
	v_lshl_add_u64 v[94:95], v[94:95], 0, v[148:149]
	s_waitcnt vmcnt(20)
	v_lshlrev_b32_e32 v96, 16, v188
	v_and_b32_e32 v97, 0xffff0000, v188
	v_lshlrev_b32_e32 v88, 16, v189
	v_and_b32_e32 v89, 0xffff0000, v189
	v_lshlrev_b32_e32 v98, 16, v190
	v_and_b32_e32 v99, 0xffff0000, v190
	v_lshlrev_b32_e32 v90, 16, v191
	v_and_b32_e32 v91, 0xffff0000, v191
	v_pk_fma_f32 v[86:87], v[86:87], 0.5, v[88:89] op_sel_hi:[1,0,1]
	v_pk_fma_f32 v[84:85], v[84:85], 0.5, v[96:97] op_sel_hi:[1,0,1]
	v_pk_fma_f32 v[82:83], v[82:83], 0.5, v[90:91] op_sel_hi:[1,0,1]
	v_pk_fma_f32 v[80:81], v[80:81], 0.5, v[98:99] op_sel_hi:[1,0,1]
	global_store_dwordx4 v[100:101], v[84:87], off offset:512 nt
	global_store_dwordx4 v[100:101], v[80:83], off offset:528 nt
	s_nop 0
	v_lshlrev_b64 v[84:85], 12, v[92:93]
	v_lshl_add_u64 v[84:85], s[48:49], 0, v[84:85]
	v_lshl_add_u64 v[84:85], v[84:85], 0, v[144:145]
	s_waitcnt vmcnt(21)
	v_lshlrev_b32_e32 v86, 16, v192
	v_and_b32_e32 v87, 0xffff0000, v192
	v_lshlrev_b32_e32 v80, 16, v193
	v_and_b32_e32 v81, 0xffff0000, v193
	v_lshlrev_b32_e32 v88, 16, v194
	v_and_b32_e32 v89, 0xffff0000, v194
	v_lshlrev_b32_e32 v82, 16, v195
	v_and_b32_e32 v83, 0xffff0000, v195
	v_pk_fma_f32 v[78:79], v[78:79], 0.5, v[80:81] op_sel_hi:[1,0,1]
	v_pk_fma_f32 v[76:77], v[76:77], 0.5, v[86:87] op_sel_hi:[1,0,1]
	v_pk_fma_f32 v[74:75], v[74:75], 0.5, v[82:83] op_sel_hi:[1,0,1]
	v_pk_fma_f32 v[72:73], v[72:73], 0.5, v[88:89] op_sel_hi:[1,0,1]
	global_store_dwordx4 v[84:85], v[76:79], off nt
	global_store_dwordx4 v[84:85], v[72:75], off offset:16 nt
	s_nop 0
	v_add_u32_e32 v76, 0x80, v146
	v_ashrrev_i32_e32 v77, 31, v76
	v_lshlrev_b64 v[78:79], 11, v[76:77]
	v_lshl_add_u64 v[78:79], s[92:93], 0, v[78:79]
	v_lshl_add_u64 v[78:79], v[78:79], 0, v[148:149]
	s_waitcnt vmcnt(22)
	v_lshlrev_b32_e32 v80, 16, v196
	v_and_b32_e32 v81, 0xffff0000, v196
	v_lshlrev_b32_e32 v72, 16, v197
	v_and_b32_e32 v73, 0xffff0000, v197
	v_lshlrev_b32_e32 v82, 16, v198
	v_and_b32_e32 v83, 0xffff0000, v198
	v_lshlrev_b32_e32 v74, 16, v199
	v_and_b32_e32 v75, 0xffff0000, v199
	v_pk_fma_f32 v[70:71], v[70:71], 0.5, v[72:73] op_sel_hi:[1,0,1]
	v_pk_fma_f32 v[68:69], v[68:69], 0.5, v[80:81] op_sel_hi:[1,0,1]
	v_pk_fma_f32 v[66:67], v[66:67], 0.5, v[74:75] op_sel_hi:[1,0,1]
	v_pk_fma_f32 v[64:65], v[64:65], 0.5, v[82:83] op_sel_hi:[1,0,1]
	global_store_dwordx4 v[84:85], v[68:71], off offset:512 nt
	global_store_dwordx4 v[84:85], v[64:67], off offset:528 nt
	s_nop 0
	v_lshlrev_b64 v[68:69], 12, v[76:77]
	v_lshl_add_u64 v[68:69], s[48:49], 0, v[68:69]
	v_lshl_add_u64 v[68:69], v[68:69], 0, v[144:145]
	s_waitcnt vmcnt(23)
	v_lshlrev_b32_e32 v70, 16, v200
	v_and_b32_e32 v71, 0xffff0000, v200
	v_lshlrev_b32_e32 v64, 16, v201
	v_and_b32_e32 v65, 0xffff0000, v201
	v_lshlrev_b32_e32 v72, 16, v202
	v_and_b32_e32 v73, 0xffff0000, v202
	v_lshlrev_b32_e32 v66, 16, v203
	v_and_b32_e32 v67, 0xffff0000, v203
	v_pk_fma_f32 v[62:63], v[62:63], 0.5, v[64:65] op_sel_hi:[1,0,1]
	v_pk_fma_f32 v[60:61], v[60:61], 0.5, v[70:71] op_sel_hi:[1,0,1]
	v_pk_fma_f32 v[58:59], v[58:59], 0.5, v[66:67] op_sel_hi:[1,0,1]
	v_pk_fma_f32 v[56:57], v[56:57], 0.5, v[72:73] op_sel_hi:[1,0,1]
	global_store_dwordx4 v[68:69], v[60:63], off nt
	global_store_dwordx4 v[68:69], v[56:59], off offset:16 nt
	s_nop 0
	v_add_u32_e32 v60, 0x90, v146
	v_ashrrev_i32_e32 v61, 31, v60
	v_lshlrev_b64 v[62:63], 11, v[60:61]
	v_lshl_add_u64 v[62:63], s[92:93], 0, v[62:63]
	v_lshl_add_u64 v[62:63], v[62:63], 0, v[148:149]
	s_waitcnt vmcnt(24)
	v_lshlrev_b32_e32 v64, 16, v204
	v_and_b32_e32 v65, 0xffff0000, v204
	v_lshlrev_b32_e32 v56, 16, v205
	v_and_b32_e32 v57, 0xffff0000, v205
	v_lshlrev_b32_e32 v66, 16, v206
	v_and_b32_e32 v67, 0xffff0000, v206
	v_lshlrev_b32_e32 v58, 16, v207
	v_and_b32_e32 v59, 0xffff0000, v207
	v_pk_fma_f32 v[54:55], v[54:55], 0.5, v[56:57] op_sel_hi:[1,0,1]
	v_pk_fma_f32 v[52:53], v[52:53], 0.5, v[64:65] op_sel_hi:[1,0,1]
	v_pk_fma_f32 v[50:51], v[50:51], 0.5, v[58:59] op_sel_hi:[1,0,1]
	v_pk_fma_f32 v[48:49], v[48:49], 0.5, v[66:67] op_sel_hi:[1,0,1]
	global_store_dwordx4 v[68:69], v[52:55], off offset:512 nt
	global_store_dwordx4 v[68:69], v[48:51], off offset:528 nt
	s_nop 0
	v_lshlrev_b64 v[52:53], 12, v[60:61]
	v_lshl_add_u64 v[52:53], s[48:49], 0, v[52:53]
	v_lshl_add_u64 v[52:53], v[52:53], 0, v[144:145]
	s_waitcnt vmcnt(25)
	v_lshlrev_b32_e32 v54, 16, v208
	v_and_b32_e32 v55, 0xffff0000, v208
	v_lshlrev_b32_e32 v48, 16, v209
	v_and_b32_e32 v49, 0xffff0000, v209
	v_lshlrev_b32_e32 v56, 16, v210
	v_and_b32_e32 v57, 0xffff0000, v210
	v_lshlrev_b32_e32 v50, 16, v211
	v_and_b32_e32 v51, 0xffff0000, v211
	v_pk_fma_f32 v[46:47], v[46:47], 0.5, v[48:49] op_sel_hi:[1,0,1]
	v_pk_fma_f32 v[44:45], v[44:45], 0.5, v[54:55] op_sel_hi:[1,0,1]
	v_pk_fma_f32 v[42:43], v[42:43], 0.5, v[50:51] op_sel_hi:[1,0,1]
	v_pk_fma_f32 v[40:41], v[40:41], 0.5, v[56:57] op_sel_hi:[1,0,1]
	global_store_dwordx4 v[52:53], v[44:47], off nt
	global_store_dwordx4 v[52:53], v[40:43], off offset:16 nt
	s_nop 0
	v_add_u32_e32 v44, 0xa0, v146
	v_ashrrev_i32_e32 v45, 31, v44
	v_lshlrev_b64 v[46:47], 11, v[44:45]
	v_lshl_add_u64 v[46:47], s[92:93], 0, v[46:47]
	v_lshl_add_u64 v[46:47], v[46:47], 0, v[148:149]
	s_waitcnt vmcnt(26)
	v_lshlrev_b32_e32 v48, 16, v212
	v_and_b32_e32 v49, 0xffff0000, v212
	v_lshlrev_b32_e32 v40, 16, v213
	v_and_b32_e32 v41, 0xffff0000, v213
	v_lshlrev_b32_e32 v50, 16, v214
	v_and_b32_e32 v51, 0xffff0000, v214
	v_lshlrev_b32_e32 v42, 16, v215
	v_and_b32_e32 v43, 0xffff0000, v215
	v_pk_fma_f32 v[38:39], v[38:39], 0.5, v[40:41] op_sel_hi:[1,0,1]
	v_pk_fma_f32 v[36:37], v[36:37], 0.5, v[48:49] op_sel_hi:[1,0,1]
	v_pk_fma_f32 v[34:35], v[34:35], 0.5, v[42:43] op_sel_hi:[1,0,1]
	v_pk_fma_f32 v[32:33], v[32:33], 0.5, v[50:51] op_sel_hi:[1,0,1]
	global_store_dwordx4 v[52:53], v[36:39], off offset:512 nt
	global_store_dwordx4 v[52:53], v[32:35], off offset:528 nt
	s_nop 0
	v_lshlrev_b64 v[36:37], 12, v[44:45]
	v_lshl_add_u64 v[36:37], s[48:49], 0, v[36:37]
	v_lshl_add_u64 v[36:37], v[36:37], 0, v[144:145]
	s_waitcnt vmcnt(27)
	v_lshlrev_b32_e32 v38, 16, v220
	v_and_b32_e32 v39, 0xffff0000, v220
	v_lshlrev_b32_e32 v32, 16, v221
	v_and_b32_e32 v33, 0xffff0000, v221
	v_lshlrev_b32_e32 v40, 16, v222
	v_and_b32_e32 v41, 0xffff0000, v222
	v_lshlrev_b32_e32 v34, 16, v223
	v_and_b32_e32 v35, 0xffff0000, v223
	v_pk_fma_f32 v[30:31], v[30:31], 0.5, v[32:33] op_sel_hi:[1,0,1]
	v_pk_fma_f32 v[28:29], v[28:29], 0.5, v[38:39] op_sel_hi:[1,0,1]
	v_pk_fma_f32 v[26:27], v[26:27], 0.5, v[34:35] op_sel_hi:[1,0,1]
	v_pk_fma_f32 v[24:25], v[24:25], 0.5, v[40:41] op_sel_hi:[1,0,1]
	global_store_dwordx4 v[36:37], v[28:31], off nt
	global_store_dwordx4 v[36:37], v[24:27], off offset:16 nt
	s_nop 0
	v_add_u32_e32 v28, 0xb0, v146
	v_ashrrev_i32_e32 v29, 31, v28
	v_lshlrev_b64 v[30:31], 11, v[28:29]
	v_lshl_add_u64 v[30:31], s[92:93], 0, v[30:31]
	v_lshl_add_u64 v[30:31], v[30:31], 0, v[148:149]
	s_waitcnt vmcnt(28)
	v_lshlrev_b32_e32 v32, 16, v224
	v_and_b32_e32 v33, 0xffff0000, v224
	v_lshlrev_b32_e32 v24, 16, v225
	v_and_b32_e32 v25, 0xffff0000, v225
	v_lshlrev_b32_e32 v34, 16, v226
	v_and_b32_e32 v35, 0xffff0000, v226
	v_lshlrev_b32_e32 v26, 16, v227
	v_and_b32_e32 v27, 0xffff0000, v227
	v_pk_fma_f32 v[22:23], v[22:23], 0.5, v[24:25] op_sel_hi:[1,0,1]
	v_pk_fma_f32 v[20:21], v[20:21], 0.5, v[32:33] op_sel_hi:[1,0,1]
	v_pk_fma_f32 v[18:19], v[18:19], 0.5, v[26:27] op_sel_hi:[1,0,1]
	v_pk_fma_f32 v[16:17], v[16:17], 0.5, v[34:35] op_sel_hi:[1,0,1]
	global_store_dwordx4 v[36:37], v[20:23], off offset:512 nt
	global_store_dwordx4 v[36:37], v[16:19], off offset:528 nt
	s_nop 0
	v_lshlrev_b64 v[20:21], 12, v[28:29]
	v_lshl_add_u64 v[20:21], s[48:49], 0, v[20:21]
	v_lshl_add_u64 v[20:21], v[20:21], 0, v[144:145]
	s_waitcnt vmcnt(29)
	v_lshlrev_b32_e32 v22, 16, v228
	v_and_b32_e32 v23, 0xffff0000, v228
	v_lshlrev_b32_e32 v16, 16, v229
	v_and_b32_e32 v17, 0xffff0000, v229
	v_lshlrev_b32_e32 v24, 16, v230
	v_and_b32_e32 v25, 0xffff0000, v230
	v_lshlrev_b32_e32 v18, 16, v231
	v_and_b32_e32 v19, 0xffff0000, v231
	v_pk_fma_f32 v[14:15], v[14:15], 0.5, v[16:17] op_sel_hi:[1,0,1]
	v_pk_fma_f32 v[12:13], v[12:13], 0.5, v[22:23] op_sel_hi:[1,0,1]
	v_pk_fma_f32 v[10:11], v[10:11], 0.5, v[18:19] op_sel_hi:[1,0,1]
	v_pk_fma_f32 v[8:9], v[8:9], 0.5, v[24:25] op_sel_hi:[1,0,1]
	global_store_dwordx4 v[20:21], v[12:15], off nt
	global_store_dwordx4 v[20:21], v[8:11], off offset:16 nt
	s_nop 0
	s_waitcnt vmcnt(30)
	v_lshlrev_b32_e32 v12, 16, v232
	v_and_b32_e32 v13, 0xffff0000, v232
	v_lshlrev_b32_e32 v8, 16, v233
	v_and_b32_e32 v9, 0xffff0000, v233
	v_lshlrev_b32_e32 v14, 16, v234
	v_and_b32_e32 v15, 0xffff0000, v234
	v_lshlrev_b32_e32 v10, 16, v235
	v_and_b32_e32 v11, 0xffff0000, v235
	v_pk_fma_f32 v[6:7], v[6:7], 0.5, v[8:9] op_sel_hi:[1,0,1]
	v_pk_fma_f32 v[4:5], v[4:5], 0.5, v[12:13] op_sel_hi:[1,0,1]
	v_pk_fma_f32 v[2:3], v[2:3], 0.5, v[10:11] op_sel_hi:[1,0,1]
	v_pk_fma_f32 v[0:1], v[0:1], 0.5, v[14:15] op_sel_hi:[1,0,1]
	global_store_dwordx4 v[20:21], v[4:7], off offset:512 nt
	global_store_dwordx4 v[20:21], v[0:3], off offset:528 nt
	s_cbranch_vccnz .LBB0_2025
	s_andn2_b64 vcc, exec, s[4:5]
	s_cbranch_vccnz .LBB0_2024
	s_barrier
	s_branch .LBB0_2024
